# v58 + barrier-approach priority also in diff-attention loop and merge GEMM segments (all LDS-staged MFMA segments)
# baseline (speedup 1.0000x reference)
.Ldq0_p0_nores:
	v_sub_f32_e32 v250, v98, v149
	v_exp_f32_e32 v98, v250
	v_sub_f32_e32 v159, v99, v149
	v_exp_f32_e32 v99, v159
	v_sub_f32_e32 v250, v100, v149
	v_exp_f32_e32 v100, v250
	v_sub_f32_e32 v159, v101, v149
	v_exp_f32_e32 v101, v159
	v_sub_f32_e32 v250, v102, v149
	v_exp_f32_e32 v102, v250
	v_sub_f32_e32 v159, v103, v149
	v_exp_f32_e32 v103, v159
	v_sub_f32_e32 v250, v104, v149
	v_exp_f32_e32 v104, v250
	v_sub_f32_e32 v159, v105, v149
	v_exp_f32_e32 v105, v159
	v_add_f32_e32 v12, v12, v98
	v_add_f32_e32 v157, v157, v99
	v_add_f32_e32 v12, v12, v100
	v_add_f32_e32 v157, v157, v101
	v_add_f32_e32 v12, v12, v102
	v_add_f32_e32 v157, v157, v103
	v_add_f32_e32 v12, v12, v104
	v_add_f32_e32 v157, v157, v105
	v_cvt_pk_bf16_f32 v98, v98, v99
	v_cvt_pk_bf16_f32 v99, v100, v101
	v_cvt_pk_bf16_f32 v100, v102, v103
	v_cvt_pk_bf16_f32 v101, v104, v105
	ds_read_b128 v[14:17], v174 offset:34848
	s_waitcnt lgkmcnt(4)
	v_mfma_f32_32x32x16_bf16 v[66:81], v[208:211], v[98:101], v[66:81]
	v_sub_f32_e32 v250, v106, v149
	v_exp_f32_e32 v106, v250
	v_sub_f32_e32 v159, v107, v149
	v_exp_f32_e32 v107, v159
	v_sub_f32_e32 v250, v108, v149
	v_exp_f32_e32 v108, v250
	v_sub_f32_e32 v159, v109, v149
	v_exp_f32_e32 v109, v159
	ds_read_b128 v[208:211], v174 offset:39456
	s_waitcnt lgkmcnt(4)
	v_mfma_f32_32x32x16_bf16 v[50:65], v[252:255], v[98:101], v[50:65]
	v_sub_f32_e32 v250, v110, v149
	v_exp_f32_e32 v110, v250
	v_sub_f32_e32 v159, v111, v149
	v_exp_f32_e32 v111, v159
	v_sub_f32_e32 v250, v112, v149
	v_exp_f32_e32 v112, v250
	v_sub_f32_e32 v159, v113, v149
	v_exp_f32_e32 v113, v159
	ds_read_b128 v[252:255], v174 offset:44064
	s_waitcnt lgkmcnt(4)
	v_mfma_f32_32x32x16_bf16 v[34:49], v[4:7], v[98:101], v[34:49]
	v_add_f32_e32 v12, v12, v106
	v_add_f32_e32 v157, v157, v107
	v_add_f32_e32 v12, v12, v108
	v_add_f32_e32 v157, v157, v109
	v_add_f32_e32 v12, v12, v110
	v_add_f32_e32 v157, v157, v111
	v_add_f32_e32 v12, v12, v112
	v_add_f32_e32 v157, v157, v113
	ds_read_b128 v[4:7], v174 offset:48672
	s_waitcnt lgkmcnt(4)
	v_mfma_f32_32x32x16_bf16 v[18:33], v[8:11], v[98:101], v[18:33]
	v_cvt_pk_bf16_f32 v106, v106, v107
	v_cvt_pk_bf16_f32 v107, v108, v109
	v_cvt_pk_bf16_f32 v108, v110, v111
	v_cvt_pk_bf16_f32 v109, v112, v113
	ds_read_b128 v[8:11], v174 offset:34880
	s_waitcnt lgkmcnt(4)
	v_mfma_f32_32x32x16_bf16 v[66:81], v[14:17], v[106:109], v[66:81]
	v_sub_f32_e32 v250, v82, v149
	v_exp_f32_e32 v82, v250
	v_sub_f32_e32 v159, v83, v149
	v_exp_f32_e32 v83, v159
	v_sub_f32_e32 v250, v84, v149
	v_exp_f32_e32 v84, v250
	v_sub_f32_e32 v159, v85, v149
	v_exp_f32_e32 v85, v159
	ds_read_b128 v[14:17], v174 offset:39488
	s_waitcnt lgkmcnt(4)
	v_mfma_f32_32x32x16_bf16 v[50:65], v[208:211], v[106:109], v[50:65]
	v_sub_f32_e32 v250, v86, v149
	v_exp_f32_e32 v86, v250
	v_sub_f32_e32 v159, v87, v149
	v_exp_f32_e32 v87, v159
	v_sub_f32_e32 v250, v88, v149
	v_exp_f32_e32 v88, v250
	v_sub_f32_e32 v159, v89, v149
	v_exp_f32_e32 v89, v159
	ds_read_b128 v[208:211], v174 offset:44096
	s_waitcnt lgkmcnt(4)
	v_mfma_f32_32x32x16_bf16 v[34:49], v[252:255], v[106:109], v[34:49]
	v_add_f32_e32 v12, v12, v82
	v_add_f32_e32 v157, v157, v83
	v_add_f32_e32 v12, v12, v84
	v_add_f32_e32 v157, v157, v85
	v_add_f32_e32 v12, v12, v86
	v_add_f32_e32 v157, v157, v87
	v_add_f32_e32 v12, v12, v88
	v_add_f32_e32 v157, v157, v89
	ds_read_b128 v[252:255], v174 offset:48704
	s_waitcnt lgkmcnt(4)
	v_mfma_f32_32x32x16_bf16 v[18:33], v[4:7], v[106:109], v[18:33]
	v_cvt_pk_bf16_f32 v82, v82, v83
	v_cvt_pk_bf16_f32 v83, v84, v85
	v_cvt_pk_bf16_f32 v84, v86, v87
	v_cvt_pk_bf16_f32 v85, v88, v89
	ds_read_b128 v[4:7], v174 offset:34912
	s_waitcnt lgkmcnt(4)
	v_mfma_f32_32x32x16_bf16 v[66:81], v[8:11], v[82:85], v[66:81]
	v_sub_f32_e32 v250, v90, v149
	v_exp_f32_e32 v90, v250
	v_sub_f32_e32 v159, v91, v149
	v_exp_f32_e32 v91, v159
	v_sub_f32_e32 v250, v92, v149
	v_exp_f32_e32 v92, v250
	v_sub_f32_e32 v159, v93, v149
	v_exp_f32_e32 v93, v159
	ds_read_b128 v[8:11], v174 offset:39520
	s_waitcnt lgkmcnt(4)
	v_mfma_f32_32x32x16_bf16 v[50:65], v[14:17], v[82:85], v[50:65]
	v_sub_f32_e32 v250, v94, v149
	v_exp_f32_e32 v94, v250
	v_sub_f32_e32 v159, v95, v149
	v_exp_f32_e32 v95, v159
	v_sub_f32_e32 v250, v96, v149
	v_exp_f32_e32 v96, v250
	v_sub_f32_e32 v159, v97, v149
	v_exp_f32_e32 v97, v159
	s_setprio 1
	s_waitcnt vmcnt(7)
	ds_write_b128 v167, v[212:215] offset:17408
	s_waitcnt vmcnt(6)
	ds_write_b128 v169, v[216:219] offset:53248
	ds_read_b128 v[14:17], v174 offset:44128
	s_waitcnt lgkmcnt(6)
	v_mfma_f32_32x32x16_bf16 v[34:49], v[208:211], v[82:85], v[34:49]
	v_add_f32_e32 v12, v12, v90
	v_add_f32_e32 v157, v157, v91
	v_add_f32_e32 v12, v12, v92
	v_add_f32_e32 v157, v157, v93
	v_add_f32_e32 v12, v12, v94
	v_add_f32_e32 v157, v157, v95
	v_add_f32_e32 v12, v12, v96
	v_add_f32_e32 v157, v157, v97
	ds_read_b128 v[208:211], v174 offset:48736
	s_waitcnt lgkmcnt(6)
	v_mfma_f32_32x32x16_bf16 v[18:33], v[252:255], v[82:85], v[18:33]
	v_cvt_pk_bf16_f32 v90, v90, v91
	v_cvt_pk_bf16_f32 v91, v92, v93
	v_cvt_pk_bf16_f32 v92, v94, v95
	v_cvt_pk_bf16_f32 v93, v96, v97
	s_waitcnt vmcnt(5)
	ds_write_b128 v182, v[220:223] offset:17408
	s_waitcnt vmcnt(4)
	ds_write_b128 v185, v[224:227] offset:53248
	s_waitcnt lgkmcnt(7)
	v_mfma_f32_32x32x16_bf16 v[66:81], v[4:7], v[90:93], v[66:81]
	s_waitcnt vmcnt(3)
	ds_write_b128 v187, v[228:231] offset:17408
	s_waitcnt vmcnt(2)
	ds_write_b128 v190, v[232:235] offset:53248
	s_waitcnt lgkmcnt(8)
	v_mfma_f32_32x32x16_bf16 v[50:65], v[8:11], v[90:93], v[50:65]
	s_waitcnt lgkmcnt(5)
	v_mfma_f32_32x32x16_bf16 v[34:49], v[14:17], v[90:93], v[34:49]
	s_waitcnt vmcnt(1)
	ds_write_b128 v170, v[236:239] offset:17408
	s_waitcnt vmcnt(0)
	ds_write_b128 v172, v[240:243] offset:53248
	s_waitcnt lgkmcnt(6)
	v_mfma_f32_32x32x16_bf16 v[18:33], v[208:211], v[90:93], v[18:33]
	s_waitcnt lgkmcnt(0)
	s_barrier
	s_setprio 0
	s_cmp_eq_u32 s38, s41
	s_cbranch_scc1 .Ldq0_exit
	s_mov_b32 s42, s41

.Ldq0_p1_nores:
	v_sub_f32_e32 v250, v98, v149
	v_exp_f32_e32 v98, v250
	v_sub_f32_e32 v159, v99, v149
	v_exp_f32_e32 v99, v159
	v_sub_f32_e32 v250, v100, v149
	v_exp_f32_e32 v100, v250
	v_sub_f32_e32 v159, v101, v149
	v_exp_f32_e32 v101, v159
	v_sub_f32_e32 v250, v102, v149
	v_exp_f32_e32 v102, v250
	v_sub_f32_e32 v159, v103, v149
	v_exp_f32_e32 v103, v159
	v_sub_f32_e32 v250, v104, v149
	v_exp_f32_e32 v104, v250
	v_sub_f32_e32 v159, v105, v149
	v_exp_f32_e32 v105, v159
	v_add_f32_e32 v12, v12, v98
	v_add_f32_e32 v157, v157, v99
	v_add_f32_e32 v12, v12, v100
	v_add_f32_e32 v157, v157, v101
	v_add_f32_e32 v12, v12, v102
	v_add_f32_e32 v157, v157, v103
	v_add_f32_e32 v12, v12, v104
	v_add_f32_e32 v157, v157, v105
	v_cvt_pk_bf16_f32 v98, v98, v99
	v_cvt_pk_bf16_f32 v99, v100, v101
	v_cvt_pk_bf16_f32 v100, v102, v103
	v_cvt_pk_bf16_f32 v101, v104, v105
	ds_read_b128 v[14:17], v206 offset:34848
	s_waitcnt lgkmcnt(4)
	v_mfma_f32_32x32x16_bf16 v[66:81], v[208:211], v[98:101], v[66:81]
	v_sub_f32_e32 v250, v106, v149
	v_exp_f32_e32 v106, v250
	v_sub_f32_e32 v159, v107, v149
	v_exp_f32_e32 v107, v159
	v_sub_f32_e32 v250, v108, v149
	v_exp_f32_e32 v108, v250
	v_sub_f32_e32 v159, v109, v149
	v_exp_f32_e32 v109, v159
	ds_read_b128 v[208:211], v206 offset:39456
	s_waitcnt lgkmcnt(4)
	v_mfma_f32_32x32x16_bf16 v[50:65], v[252:255], v[98:101], v[50:65]
	v_sub_f32_e32 v250, v110, v149
	v_exp_f32_e32 v110, v250
	v_sub_f32_e32 v159, v111, v149
	v_exp_f32_e32 v111, v159
	v_sub_f32_e32 v250, v112, v149
	v_exp_f32_e32 v112, v250
	v_sub_f32_e32 v159, v113, v149
	v_exp_f32_e32 v113, v159
	ds_read_b128 v[252:255], v206 offset:44064
	s_waitcnt lgkmcnt(4)
	v_mfma_f32_32x32x16_bf16 v[34:49], v[4:7], v[98:101], v[34:49]
	v_add_f32_e32 v12, v12, v106
	v_add_f32_e32 v157, v157, v107
	v_add_f32_e32 v12, v12, v108
	v_add_f32_e32 v157, v157, v109
	v_add_f32_e32 v12, v12, v110
	v_add_f32_e32 v157, v157, v111
	v_add_f32_e32 v12, v12, v112
	v_add_f32_e32 v157, v157, v113
	ds_read_b128 v[4:7], v206 offset:48672
	s_waitcnt lgkmcnt(4)
	v_mfma_f32_32x32x16_bf16 v[18:33], v[8:11], v[98:101], v[18:33]
	v_cvt_pk_bf16_f32 v106, v106, v107
	v_cvt_pk_bf16_f32 v107, v108, v109
	v_cvt_pk_bf16_f32 v108, v110, v111
	v_cvt_pk_bf16_f32 v109, v112, v113
	ds_read_b128 v[8:11], v206 offset:34880
	s_waitcnt lgkmcnt(4)
	v_mfma_f32_32x32x16_bf16 v[66:81], v[14:17], v[106:109], v[66:81]
	v_sub_f32_e32 v250, v82, v149
	v_exp_f32_e32 v82, v250
	v_sub_f32_e32 v159, v83, v149
	v_exp_f32_e32 v83, v159
	v_sub_f32_e32 v250, v84, v149
	v_exp_f32_e32 v84, v250
	v_sub_f32_e32 v159, v85, v149
	v_exp_f32_e32 v85, v159
	ds_read_b128 v[14:17], v206 offset:39488
	s_waitcnt lgkmcnt(4)
	v_mfma_f32_32x32x16_bf16 v[50:65], v[208:211], v[106:109], v[50:65]
	v_sub_f32_e32 v250, v86, v149
	v_exp_f32_e32 v86, v250
	v_sub_f32_e32 v159, v87, v149
	v_exp_f32_e32 v87, v159
	v_sub_f32_e32 v250, v88, v149
	v_exp_f32_e32 v88, v250
	v_sub_f32_e32 v159, v89, v149
	v_exp_f32_e32 v89, v159
	ds_read_b128 v[208:211], v206 offset:44096
	s_waitcnt lgkmcnt(4)
	v_mfma_f32_32x32x16_bf16 v[34:49], v[252:255], v[106:109], v[34:49]
	v_add_f32_e32 v12, v12, v82
	v_add_f32_e32 v157, v157, v83
	v_add_f32_e32 v12, v12, v84
	v_add_f32_e32 v157, v157, v85
	v_add_f32_e32 v12, v12, v86
	v_add_f32_e32 v157, v157, v87
	v_add_f32_e32 v12, v12, v88
	v_add_f32_e32 v157, v157, v89
	ds_read_b128 v[252:255], v206 offset:48704
	s_waitcnt lgkmcnt(4)
	v_mfma_f32_32x32x16_bf16 v[18:33], v[4:7], v[106:109], v[18:33]
	v_cvt_pk_bf16_f32 v82, v82, v83
	v_cvt_pk_bf16_f32 v83, v84, v85
	v_cvt_pk_bf16_f32 v84, v86, v87
	v_cvt_pk_bf16_f32 v85, v88, v89
	ds_read_b128 v[4:7], v206 offset:34912
	s_waitcnt lgkmcnt(4)
	v_mfma_f32_32x32x16_bf16 v[66:81], v[8:11], v[82:85], v[66:81]
	v_sub_f32_e32 v250, v90, v149
	v_exp_f32_e32 v90, v250
	v_sub_f32_e32 v159, v91, v149
	v_exp_f32_e32 v91, v159
	v_sub_f32_e32 v250, v92, v149
	v_exp_f32_e32 v92, v250
	v_sub_f32_e32 v159, v93, v149
	v_exp_f32_e32 v93, v159
	ds_read_b128 v[8:11], v206 offset:39520
	s_waitcnt lgkmcnt(4)
	v_mfma_f32_32x32x16_bf16 v[50:65], v[14:17], v[82:85], v[50:65]
	v_sub_f32_e32 v250, v94, v149
	v_exp_f32_e32 v94, v250
	v_sub_f32_e32 v159, v95, v149
	v_exp_f32_e32 v95, v159
	v_sub_f32_e32 v250, v96, v149
	v_exp_f32_e32 v96, v250
	v_sub_f32_e32 v159, v97, v149
	v_exp_f32_e32 v97, v159
	s_setprio 1
	s_waitcnt vmcnt(7)
	ds_write_b128 v167, v[212:215]
	s_waitcnt vmcnt(6)
	ds_write_b128 v169, v[216:219] offset:34816
	ds_read_b128 v[14:17], v206 offset:44128
	s_waitcnt lgkmcnt(6)
	v_mfma_f32_32x32x16_bf16 v[34:49], v[208:211], v[82:85], v[34:49]
	v_add_f32_e32 v12, v12, v90
	v_add_f32_e32 v157, v157, v91
	v_add_f32_e32 v12, v12, v92
	v_add_f32_e32 v157, v157, v93
	v_add_f32_e32 v12, v12, v94
	v_add_f32_e32 v157, v157, v95
	v_add_f32_e32 v12, v12, v96
	v_add_f32_e32 v157, v157, v97
	ds_read_b128 v[208:211], v206 offset:48736
	s_waitcnt lgkmcnt(6)
	v_mfma_f32_32x32x16_bf16 v[18:33], v[252:255], v[82:85], v[18:33]
	v_cvt_pk_bf16_f32 v90, v90, v91
	v_cvt_pk_bf16_f32 v91, v92, v93
	v_cvt_pk_bf16_f32 v92, v94, v95
	v_cvt_pk_bf16_f32 v93, v96, v97
	s_waitcnt vmcnt(5)
	ds_write_b128 v182, v[220:223]
	s_waitcnt vmcnt(4)
	ds_write_b128 v185, v[224:227] offset:34816
	s_waitcnt lgkmcnt(7)
	v_mfma_f32_32x32x16_bf16 v[66:81], v[4:7], v[90:93], v[66:81]
	s_waitcnt vmcnt(3)
	ds_write_b128 v187, v[228:231]
	s_waitcnt vmcnt(2)
	ds_write_b128 v190, v[232:235] offset:34816
	s_waitcnt lgkmcnt(8)
	v_mfma_f32_32x32x16_bf16 v[50:65], v[8:11], v[90:93], v[50:65]
	s_waitcnt lgkmcnt(5)
	v_mfma_f32_32x32x16_bf16 v[34:49], v[14:17], v[90:93], v[34:49]
	s_waitcnt vmcnt(1)
	ds_write_b128 v170, v[236:239]
	s_waitcnt vmcnt(0)
	ds_write_b128 v172, v[240:243] offset:34816
	s_waitcnt lgkmcnt(6)
	v_mfma_f32_32x32x16_bf16 v[18:33], v[208:211], v[90:93], v[18:33]
	s_waitcnt lgkmcnt(0)
	s_barrier
	s_setprio 0
	s_cmp_eq_u32 s38, s41
	s_cbranch_scc1 .Ldq0_exit
	s_mov_b32 s42, s41
	s_branch .Ldq0_p0_top

.LBB0_903:
	s_cmp_eq_u32 s2, 0x100000
	s_cselect_b32 s0, s13, 0x5400000
	s_cmp_lg_u32 s2, 0
	v_lshl_add_u64 v[2:3], v[152:153], 0, s[2:3]
	s_cselect_b32 s0, s0, 0
	v_add_co_u32_e32 v178, vcc, s14, v2
	s_add_u32 s4, s82, s0
	v_lshl_add_u64 v[4:5], v[156:157], 0, s[2:3]
	v_addc_co_u32_e32 v179, vcc, 0, v3, vcc
	s_addc_u32 s5, s83, 0
	v_add_co_u32_e32 v180, vcc, s14, v4
	v_lshl_add_u64 v[10:11], v[158:159], 0, s[2:3]
	v_lshl_add_u64 v[6:7], s[4:5], 0, v[104:105]
	v_addc_co_u32_e32 v181, vcc, 0, v5, vcc
	v_lshl_add_u64 v[66:67], v[6:7], 0, v[82:83]
	v_lshl_add_u64 v[6:7], s[4:5], 0, v[112:113]
	v_add_co_u32_e32 v182, vcc, s14, v10
	v_lshl_add_u64 v[12:13], v[160:161], 0, s[2:3]
	v_lshl_add_u64 v[70:71], v[6:7], 0, v[82:83]
	v_lshl_add_u64 v[6:7], s[4:5], 0, v[116:117]
	v_addc_co_u32_e32 v183, vcc, 0, v11, vcc
	v_lshl_add_u64 v[68:69], v[6:7], 0, v[82:83]
	v_lshl_add_u64 v[6:7], s[4:5], 0, v[120:121]
	v_add_co_u32_e32 v184, vcc, s14, v12
	v_lshl_add_u64 v[72:73], v[6:7], 0, v[82:83]
	global_load_dwordx4 v[2:5], v[178:179], off
	global_load_dwordx4 v[6:9], v[180:181], off
	v_addc_co_u32_e32 v185, vcc, 0, v13, vcc
	global_load_dwordx4 v[10:13], v[182:183], off
	global_load_dwordx4 v[14:17], v[184:185], off
	global_load_dwordx4 v[18:21], v[66:67], off
	global_load_dwordx4 v[22:25], v[70:71], off
	global_load_dwordx4 v[26:29], v[68:69], off
	global_load_dwordx4 v[30:33], v[72:73], off
	s_cmp_lt_i32 s17, 1
	s_mov_b32 s0, s11
	s_waitcnt vmcnt(7)
	ds_write_b128 v196, v[2:5]
	s_waitcnt vmcnt(6)
	ds_write_b128 v196, v[6:9] offset:4608
	s_waitcnt vmcnt(5)
	ds_write_b128 v196, v[10:13] offset:9216
	s_waitcnt vmcnt(4)
	ds_write_b128 v196, v[14:17] offset:13824
	s_waitcnt vmcnt(3)
	ds_write_b128 v196, v[18:21] offset:36864
	s_waitcnt vmcnt(2)
	ds_write_b128 v196, v[22:25] offset:41472
	s_waitcnt vmcnt(1)
	ds_write_b128 v196, v[26:29] offset:46080
	s_waitcnt vmcnt(0)
	ds_write_b128 v196, v[30:33] offset:50688
	s_waitcnt lgkmcnt(0)
	s_barrier
	ds_read_b128 v[2:5], v193
	ds_read_b128 v[6:9], v195 offset:36864
	ds_read_b128 v[202:205], v193 offset:32
	ds_read_b128 v[206:209], v195 offset:36896
	ds_read_b128 v[10:13], v193 offset:4608
	ds_read_b128 v[210:213], v193 offset:4640
	s_waitcnt lgkmcnt(4)
	v_mfma_f32_32x32x16_bf16 v[50:65], v[2:5], v[6:9], 0
	s_waitcnt lgkmcnt(1)
	v_mfma_f32_32x32x16_bf16 v[34:49], v[10:13], v[6:9], 0
	ds_read_b128 v[6:9], v195 offset:41472
	ds_read_b128 v[214:217], v195 offset:41504
	s_waitcnt lgkmcnt(1)
	v_mfma_f32_32x32x16_bf16 v[18:33], v[2:5], v[6:9], 0
	v_mfma_f32_32x32x16_bf16 v[2:17], v[10:13], v[6:9], 0
	v_mfma_f32_32x32x16_bf16 v[50:65], v[202:205], v[206:209], v[50:65]
	v_mfma_f32_32x32x16_bf16 v[34:49], v[210:213], v[206:209], v[34:49]
	s_waitcnt lgkmcnt(0)
	v_mfma_f32_32x32x16_bf16 v[18:33], v[202:205], v[214:217], v[18:33]
	v_mfma_f32_32x32x16_bf16 v[2:17], v[210:213], v[214:217], v[2:17]
	ds_read_b128 v[202:205], v193 offset:64
	ds_read_b128 v[206:209], v195 offset:36928
	ds_read_b128 v[210:213], v193 offset:96
	ds_read_b128 v[214:217], v195 offset:36960
	ds_read_b128 v[218:221], v193 offset:4672
	ds_read_b128 v[222:225], v193 offset:4704
	s_waitcnt lgkmcnt(4)
	v_mfma_f32_32x32x16_bf16 v[50:65], v[202:205], v[206:209], v[50:65]
	s_waitcnt lgkmcnt(1)
	v_mfma_f32_32x32x16_bf16 v[34:49], v[218:221], v[206:209], v[34:49]
	ds_read_b128 v[206:209], v195 offset:41536
	ds_read_b128 v[226:229], v195 offset:41568
	s_waitcnt lgkmcnt(1)
	v_mfma_f32_32x32x16_bf16 v[18:33], v[202:205], v[206:209], v[18:33]
	v_mfma_f32_32x32x16_bf16 v[2:17], v[218:221], v[206:209], v[2:17]
	v_mfma_f32_32x32x16_bf16 v[50:65], v[210:213], v[214:217], v[50:65]
	v_mfma_f32_32x32x16_bf16 v[34:49], v[222:225], v[214:217], v[34:49]
	global_load_dwordx4 v[202:205], v[178:179], off offset:128
	global_load_dwordx4 v[206:209], v[180:181], off offset:128
	global_load_dwordx4 v[214:217], v[182:183], off offset:128
	global_load_dwordx4 v[218:221], v[184:185], off offset:128
	global_load_dwordx4 v[230:233], v[66:67], off offset:128
	global_load_dwordx4 v[234:237], v[70:71], off offset:128
	s_waitcnt lgkmcnt(0)
	v_mfma_f32_32x32x16_bf16 v[18:33], v[210:213], v[226:229], v[18:33]
	global_load_dwordx4 v[210:213], v[68:69], off offset:128
	global_load_dwordx4 v[238:241], v[72:73], off offset:128
	s_setprio 1
	s_waitcnt vmcnt(7)
	ds_write_b128 v196, v[202:205] offset:18432
	s_waitcnt vmcnt(6)
	ds_write_b128 v196, v[206:209] offset:23040
	s_waitcnt vmcnt(5)
	ds_write_b128 v196, v[214:217] offset:27648
	s_waitcnt vmcnt(4)
	ds_write_b128 v196, v[218:221] offset:32256
	s_waitcnt vmcnt(3)
	ds_write_b128 v196, v[230:233] offset:55296
	s_waitcnt vmcnt(2)
	ds_write_b128 v196, v[234:237] offset:59904
	s_waitcnt vmcnt(1)
	ds_write_b128 v196, v[210:213] offset:64512
	s_waitcnt vmcnt(0)
	ds_write_b128 v197, v[238:241] offset:32256
	v_mfma_f32_32x32x16_bf16 v[2:17], v[222:225], v[226:229], v[2:17]
	s_waitcnt lgkmcnt(0)
	s_barrier
	s_setprio 0
	ds_read_b128 v[202:205], v193 offset:18432
	ds_read_b128 v[206:209], v195 offset:55296
	ds_read_b128 v[210:213], v193 offset:18464
	ds_read_b128 v[214:217], v195 offset:55328
	ds_read_b128 v[218:221], v193 offset:23040
	ds_read_b128 v[222:225], v193 offset:23072
	s_waitcnt lgkmcnt(4)
	v_mfma_f32_32x32x16_bf16 v[50:65], v[202:205], v[206:209], v[50:65]
	s_waitcnt lgkmcnt(1)
	v_mfma_f32_32x32x16_bf16 v[34:49], v[218:221], v[206:209], v[34:49]
	ds_read_b128 v[206:209], v195 offset:59904
	ds_read_b128 v[226:229], v195 offset:59936
	s_waitcnt lgkmcnt(1)
	v_mfma_f32_32x32x16_bf16 v[18:33], v[202:205], v[206:209], v[18:33]
	v_mfma_f32_32x32x16_bf16 v[2:17], v[218:221], v[206:209], v[2:17]
	v_mfma_f32_32x32x16_bf16 v[50:65], v[210:213], v[214:217], v[50:65]
	v_mfma_f32_32x32x16_bf16 v[34:49], v[222:225], v[214:217], v[34:49]
	s_waitcnt lgkmcnt(0)
	v_mfma_f32_32x32x16_bf16 v[18:33], v[210:213], v[226:229], v[18:33]
	ds_read_b128 v[202:205], v193 offset:18496
	ds_read_b128 v[206:209], v195 offset:55360
	ds_read_b128 v[210:213], v193 offset:18528
	ds_read_b128 v[214:217], v195 offset:55392
	v_mfma_f32_32x32x16_bf16 v[2:17], v[222:225], v[226:229], v[2:17]
	ds_read_b128 v[218:221], v193 offset:23104
	ds_read_b128 v[222:225], v193 offset:23136
	s_waitcnt lgkmcnt(4)
	v_mfma_f32_32x32x16_bf16 v[50:65], v[202:205], v[206:209], v[50:65]
	s_waitcnt lgkmcnt(1)
	v_mfma_f32_32x32x16_bf16 v[34:49], v[218:221], v[206:209], v[34:49]
	ds_read_b128 v[206:209], v195 offset:59968
	ds_read_b128 v[226:229], v195 offset:60000
	s_waitcnt lgkmcnt(1)
	v_mfma_f32_32x32x16_bf16 v[18:33], v[202:205], v[206:209], v[18:33]
	v_mfma_f32_32x32x16_bf16 v[2:17], v[218:221], v[206:209], v[2:17]
	v_mfma_f32_32x32x16_bf16 v[50:65], v[210:213], v[214:217], v[50:65]
	v_mfma_f32_32x32x16_bf16 v[34:49], v[222:225], v[214:217], v[34:49]
	global_load_dwordx4 v[202:205], v[178:179], off offset:256
	global_load_dwordx4 v[206:209], v[180:181], off offset:256
	global_load_dwordx4 v[214:217], v[182:183], off offset:256
	global_load_dwordx4 v[218:221], v[184:185], off offset:256
	global_load_dwordx4 v[230:233], v[66:67], off offset:256
	global_load_dwordx4 v[234:237], v[70:71], off offset:256
	s_waitcnt lgkmcnt(0)
	v_mfma_f32_32x32x16_bf16 v[18:33], v[210:213], v[226:229], v[18:33]
	global_load_dwordx4 v[210:213], v[68:69], off offset:256
	global_load_dwordx4 v[238:241], v[72:73], off offset:256
	s_setprio 1
	s_waitcnt vmcnt(7)
	ds_write_b128 v196, v[202:205]
	s_waitcnt vmcnt(6)
	ds_write_b128 v196, v[206:209] offset:4608
	s_waitcnt vmcnt(5)
	ds_write_b128 v196, v[214:217] offset:9216
	s_waitcnt vmcnt(4)
	ds_write_b128 v196, v[218:221] offset:13824
	s_waitcnt vmcnt(3)
	ds_write_b128 v196, v[230:233] offset:36864
	s_waitcnt vmcnt(2)
	ds_write_b128 v196, v[234:237] offset:41472
	s_waitcnt vmcnt(1)
	ds_write_b128 v196, v[210:213] offset:46080
	s_waitcnt vmcnt(0)
	ds_write_b128 v196, v[238:241] offset:50688
	v_mfma_f32_32x32x16_bf16 v[2:17], v[222:225], v[226:229], v[2:17]
	s_waitcnt lgkmcnt(0)
	s_barrier
	s_setprio 0
	ds_read_b128 v[202:205], v193
	ds_read_b128 v[206:209], v195 offset:36864
	ds_read_b128 v[210:213], v193 offset:32
	ds_read_b128 v[214:217], v195 offset:36896
	ds_read_b128 v[218:221], v193 offset:4608
	ds_read_b128 v[222:225], v193 offset:4640
	s_waitcnt lgkmcnt(4)
	v_mfma_f32_32x32x16_bf16 v[50:65], v[202:205], v[206:209], v[50:65]
	s_waitcnt lgkmcnt(1)
	v_mfma_f32_32x32x16_bf16 v[34:49], v[218:221], v[206:209], v[34:49]
	ds_read_b128 v[206:209], v195 offset:41472
	ds_read_b128 v[226:229], v195 offset:41504
	s_waitcnt lgkmcnt(1)
	v_mfma_f32_32x32x16_bf16 v[18:33], v[202:205], v[206:209], v[18:33]
	v_mfma_f32_32x32x16_bf16 v[2:17], v[218:221], v[206:209], v[2:17]
	v_mfma_f32_32x32x16_bf16 v[50:65], v[210:213], v[214:217], v[50:65]
	v_mfma_f32_32x32x16_bf16 v[34:49], v[222:225], v[214:217], v[34:49]
	s_waitcnt lgkmcnt(0)
	v_mfma_f32_32x32x16_bf16 v[18:33], v[210:213], v[226:229], v[18:33]
	ds_read_b128 v[202:205], v193 offset:64
	ds_read_b128 v[206:209], v195 offset:36928
	ds_read_b128 v[210:213], v193 offset:96
	ds_read_b128 v[214:217], v195 offset:36960
	v_mfma_f32_32x32x16_bf16 v[2:17], v[222:225], v[226:229], v[2:17]
	ds_read_b128 v[218:221], v193 offset:4672
	ds_read_b128 v[222:225], v193 offset:4704
	s_waitcnt lgkmcnt(4)
	v_mfma_f32_32x32x16_bf16 v[50:65], v[202:205], v[206:209], v[50:65]
	s_waitcnt lgkmcnt(1)
	v_mfma_f32_32x32x16_bf16 v[34:49], v[218:221], v[206:209], v[34:49]
	ds_read_b128 v[206:209], v195 offset:41536
	ds_read_b128 v[226:229], v195 offset:41568
	s_waitcnt lgkmcnt(1)
	v_mfma_f32_32x32x16_bf16 v[18:33], v[202:205], v[206:209], v[18:33]
	v_mfma_f32_32x32x16_bf16 v[2:17], v[218:221], v[206:209], v[2:17]
	v_mfma_f32_32x32x16_bf16 v[50:65], v[210:213], v[214:217], v[50:65]
	v_mfma_f32_32x32x16_bf16 v[34:49], v[222:225], v[214:217], v[34:49]
	global_load_dwordx4 v[202:205], v[178:179], off offset:384
	global_load_dwordx4 v[206:209], v[180:181], off offset:384
	global_load_dwordx4 v[214:217], v[182:183], off offset:384
	global_load_dwordx4 v[218:221], v[184:185], off offset:384
	global_load_dwordx4 v[230:233], v[66:67], off offset:384
	global_load_dwordx4 v[234:237], v[70:71], off offset:384
	s_waitcnt lgkmcnt(0)
	v_mfma_f32_32x32x16_bf16 v[18:33], v[210:213], v[226:229], v[18:33]
	global_load_dwordx4 v[210:213], v[68:69], off offset:384
	global_load_dwordx4 v[238:241], v[72:73], off offset:384
	s_setprio 1
	s_waitcnt vmcnt(7)
	ds_write_b128 v196, v[202:205] offset:18432
	s_waitcnt vmcnt(6)
	ds_write_b128 v196, v[206:209] offset:23040
	s_waitcnt vmcnt(5)
	ds_write_b128 v196, v[214:217] offset:27648
	s_waitcnt vmcnt(4)
	ds_write_b128 v196, v[218:221] offset:32256
	s_waitcnt vmcnt(3)
	ds_write_b128 v196, v[230:233] offset:55296
	s_waitcnt vmcnt(2)
	ds_write_b128 v196, v[234:237] offset:59904
	s_waitcnt vmcnt(1)
	ds_write_b128 v196, v[210:213] offset:64512
	s_waitcnt vmcnt(0)
	ds_write_b128 v197, v[238:241] offset:32256
	v_mfma_f32_32x32x16_bf16 v[2:17], v[222:225], v[226:229], v[2:17]
	s_waitcnt lgkmcnt(0)
	s_barrier
	s_setprio 0
	ds_read_b128 v[202:205], v193 offset:18432
	ds_read_b128 v[206:209], v195 offset:55296
	ds_read_b128 v[210:213], v193 offset:18464
	ds_read_b128 v[214:217], v195 offset:55328
	ds_read_b128 v[218:221], v193 offset:23040
	ds_read_b128 v[222:225], v193 offset:23072
	s_waitcnt lgkmcnt(4)
	v_mfma_f32_32x32x16_bf16 v[50:65], v[202:205], v[206:209], v[50:65]
	s_waitcnt lgkmcnt(1)
	v_mfma_f32_32x32x16_bf16 v[34:49], v[218:221], v[206:209], v[34:49]
	ds_read_b128 v[206:209], v195 offset:59904
	ds_read_b128 v[226:229], v195 offset:59936
	s_waitcnt lgkmcnt(1)
	v_mfma_f32_32x32x16_bf16 v[18:33], v[202:205], v[206:209], v[18:33]
	v_mfma_f32_32x32x16_bf16 v[2:17], v[218:221], v[206:209], v[2:17]
	v_mfma_f32_32x32x16_bf16 v[50:65], v[210:213], v[214:217], v[50:65]
	v_mfma_f32_32x32x16_bf16 v[34:49], v[222:225], v[214:217], v[34:49]
	s_waitcnt lgkmcnt(0)
	v_mfma_f32_32x32x16_bf16 v[18:33], v[210:213], v[226:229], v[18:33]
	ds_read_b128 v[202:205], v193 offset:18496
	ds_read_b128 v[206:209], v195 offset:55360
	ds_read_b128 v[210:213], v193 offset:18528
	ds_read_b128 v[214:217], v195 offset:55392
	v_mfma_f32_32x32x16_bf16 v[2:17], v[222:225], v[226:229], v[2:17]
	ds_read_b128 v[218:221], v193 offset:23104
	ds_read_b128 v[222:225], v193 offset:23136
	s_waitcnt lgkmcnt(4)
	v_mfma_f32_32x32x16_bf16 v[50:65], v[202:205], v[206:209], v[50:65]
	s_waitcnt lgkmcnt(1)
	v_mfma_f32_32x32x16_bf16 v[34:49], v[218:221], v[206:209], v[34:49]
	ds_read_b128 v[206:209], v195 offset:59968
	ds_read_b128 v[226:229], v195 offset:60000
	s_waitcnt lgkmcnt(1)
	v_mfma_f32_32x32x16_bf16 v[18:33], v[202:205], v[206:209], v[18:33]
	v_mfma_f32_32x32x16_bf16 v[2:17], v[218:221], v[206:209], v[2:17]
	v_mfma_f32_32x32x16_bf16 v[50:65], v[210:213], v[214:217], v[50:65]
	v_mfma_f32_32x32x16_bf16 v[34:49], v[222:225], v[214:217], v[34:49]
	global_load_dwordx4 v[202:205], v[178:179], off offset:512
	global_load_dwordx4 v[206:209], v[180:181], off offset:512
	global_load_dwordx4 v[214:217], v[182:183], off offset:512
	global_load_dwordx4 v[218:221], v[184:185], off offset:512
	global_load_dwordx4 v[230:233], v[66:67], off offset:512
	global_load_dwordx4 v[234:237], v[70:71], off offset:512
	s_waitcnt lgkmcnt(0)
	v_mfma_f32_32x32x16_bf16 v[18:33], v[210:213], v[226:229], v[18:33]
	global_load_dwordx4 v[210:213], v[68:69], off offset:512
	global_load_dwordx4 v[238:241], v[72:73], off offset:512
	s_setprio 1
	s_waitcnt vmcnt(7)
	ds_write_b128 v196, v[202:205]
	s_waitcnt vmcnt(6)
	ds_write_b128 v196, v[206:209] offset:4608
	s_waitcnt vmcnt(5)
	ds_write_b128 v196, v[214:217] offset:9216
	s_waitcnt vmcnt(4)
	ds_write_b128 v196, v[218:221] offset:13824
	s_waitcnt vmcnt(3)
	ds_write_b128 v196, v[230:233] offset:36864
	s_waitcnt vmcnt(2)
	ds_write_b128 v196, v[234:237] offset:41472
	s_waitcnt vmcnt(1)
	ds_write_b128 v196, v[210:213] offset:46080
	s_waitcnt vmcnt(0)
	ds_write_b128 v196, v[238:241] offset:50688
	v_mfma_f32_32x32x16_bf16 v[2:17], v[222:225], v[226:229], v[2:17]
	s_waitcnt lgkmcnt(0)
	s_barrier
	s_setprio 0
	ds_read_b128 v[202:205], v193
	ds_read_b128 v[206:209], v195 offset:36864
	ds_read_b128 v[210:213], v193 offset:32
	ds_read_b128 v[214:217], v195 offset:36896
	ds_read_b128 v[218:221], v193 offset:4608
	ds_read_b128 v[222:225], v193 offset:4640
	s_waitcnt lgkmcnt(4)
	v_mfma_f32_32x32x16_bf16 v[50:65], v[202:205], v[206:209], v[50:65]
	s_waitcnt lgkmcnt(1)
	v_mfma_f32_32x32x16_bf16 v[34:49], v[218:221], v[206:209], v[34:49]
	ds_read_b128 v[206:209], v195 offset:41472
	ds_read_b128 v[226:229], v195 offset:41504
	s_waitcnt lgkmcnt(1)
	v_mfma_f32_32x32x16_bf16 v[18:33], v[202:205], v[206:209], v[18:33]
	v_mfma_f32_32x32x16_bf16 v[2:17], v[218:221], v[206:209], v[2:17]
	v_mfma_f32_32x32x16_bf16 v[50:65], v[210:213], v[214:217], v[50:65]
	v_mfma_f32_32x32x16_bf16 v[34:49], v[222:225], v[214:217], v[34:49]
	s_waitcnt lgkmcnt(0)
	v_mfma_f32_32x32x16_bf16 v[18:33], v[210:213], v[226:229], v[18:33]
	ds_read_b128 v[202:205], v193 offset:64
	ds_read_b128 v[206:209], v195 offset:36928
	ds_read_b128 v[210:213], v193 offset:96
	ds_read_b128 v[214:217], v195 offset:36960
	v_mfma_f32_32x32x16_bf16 v[2:17], v[222:225], v[226:229], v[2:17]
	ds_read_b128 v[218:221], v193 offset:4672
	ds_read_b128 v[222:225], v193 offset:4704
	s_waitcnt lgkmcnt(4)
	v_mfma_f32_32x32x16_bf16 v[50:65], v[202:205], v[206:209], v[50:65]
	s_waitcnt lgkmcnt(1)
	v_mfma_f32_32x32x16_bf16 v[34:49], v[218:221], v[206:209], v[34:49]
	ds_read_b128 v[206:209], v195 offset:41536
	ds_read_b128 v[226:229], v195 offset:41568
	s_waitcnt lgkmcnt(1)
	v_mfma_f32_32x32x16_bf16 v[18:33], v[202:205], v[206:209], v[18:33]
	v_mfma_f32_32x32x16_bf16 v[2:17], v[218:221], v[206:209], v[2:17]
	v_mfma_f32_32x32x16_bf16 v[50:65], v[210:213], v[214:217], v[50:65]
	v_mfma_f32_32x32x16_bf16 v[34:49], v[222:225], v[214:217], v[34:49]
	global_load_dwordx4 v[202:205], v[178:179], off offset:640
	global_load_dwordx4 v[206:209], v[180:181], off offset:640
	global_load_dwordx4 v[214:217], v[182:183], off offset:640
	global_load_dwordx4 v[218:221], v[184:185], off offset:640
	global_load_dwordx4 v[230:233], v[66:67], off offset:640
	global_load_dwordx4 v[234:237], v[70:71], off offset:640
	s_waitcnt lgkmcnt(0)
	v_mfma_f32_32x32x16_bf16 v[18:33], v[210:213], v[226:229], v[18:33]
	global_load_dwordx4 v[210:213], v[68:69], off offset:640
	global_load_dwordx4 v[238:241], v[72:73], off offset:640
	s_setprio 1
	s_waitcnt vmcnt(7)
	ds_write_b128 v196, v[202:205] offset:18432
	s_waitcnt vmcnt(6)
	ds_write_b128 v196, v[206:209] offset:23040
	s_waitcnt vmcnt(5)
	ds_write_b128 v196, v[214:217] offset:27648
	s_waitcnt vmcnt(4)
	ds_write_b128 v196, v[218:221] offset:32256
	s_waitcnt vmcnt(3)
	ds_write_b128 v196, v[230:233] offset:55296
	s_waitcnt vmcnt(2)
	ds_write_b128 v196, v[234:237] offset:59904
	s_waitcnt vmcnt(1)
	ds_write_b128 v196, v[210:213] offset:64512
	s_waitcnt vmcnt(0)
	ds_write_b128 v197, v[238:241] offset:32256
	v_mfma_f32_32x32x16_bf16 v[2:17], v[222:225], v[226:229], v[2:17]
	s_waitcnt lgkmcnt(0)
	s_barrier
	s_setprio 0
	ds_read_b128 v[202:205], v193 offset:18432
	ds_read_b128 v[206:209], v195 offset:55296
	ds_read_b128 v[210:213], v193 offset:18464
	ds_read_b128 v[214:217], v195 offset:55328
	ds_read_b128 v[218:221], v193 offset:23040
	ds_read_b128 v[222:225], v193 offset:23072
	s_waitcnt lgkmcnt(4)
	v_mfma_f32_32x32x16_bf16 v[50:65], v[202:205], v[206:209], v[50:65]
	s_waitcnt lgkmcnt(1)
	v_mfma_f32_32x32x16_bf16 v[34:49], v[218:221], v[206:209], v[34:49]
	ds_read_b128 v[206:209], v195 offset:59904
	ds_read_b128 v[226:229], v195 offset:59936
	s_waitcnt lgkmcnt(1)
	v_mfma_f32_32x32x16_bf16 v[18:33], v[202:205], v[206:209], v[18:33]
	v_mfma_f32_32x32x16_bf16 v[2:17], v[218:221], v[206:209], v[2:17]
	v_mfma_f32_32x32x16_bf16 v[50:65], v[210:213], v[214:217], v[50:65]
	v_mfma_f32_32x32x16_bf16 v[34:49], v[222:225], v[214:217], v[34:49]
	s_waitcnt lgkmcnt(0)
	v_mfma_f32_32x32x16_bf16 v[18:33], v[210:213], v[226:229], v[18:33]
	ds_read_b128 v[202:205], v193 offset:18496
	ds_read_b128 v[206:209], v195 offset:55360
	ds_read_b128 v[210:213], v193 offset:18528
	ds_read_b128 v[214:217], v195 offset:55392
	v_mfma_f32_32x32x16_bf16 v[2:17], v[222:225], v[226:229], v[2:17]
	ds_read_b128 v[218:221], v193 offset:23104
	ds_read_b128 v[222:225], v193 offset:23136
	s_waitcnt lgkmcnt(4)
	v_mfma_f32_32x32x16_bf16 v[50:65], v[202:205], v[206:209], v[50:65]
	s_waitcnt lgkmcnt(1)
	v_mfma_f32_32x32x16_bf16 v[34:49], v[218:221], v[206:209], v[34:49]
	ds_read_b128 v[206:209], v195 offset:59968
	ds_read_b128 v[226:229], v195 offset:60000
	s_waitcnt lgkmcnt(1)
	v_mfma_f32_32x32x16_bf16 v[18:33], v[202:205], v[206:209], v[18:33]
	v_mfma_f32_32x32x16_bf16 v[2:17], v[218:221], v[206:209], v[2:17]
	v_mfma_f32_32x32x16_bf16 v[50:65], v[210:213], v[214:217], v[50:65]
	v_mfma_f32_32x32x16_bf16 v[34:49], v[222:225], v[214:217], v[34:49]
	global_load_dwordx4 v[202:205], v[178:179], off offset:768
	global_load_dwordx4 v[206:209], v[180:181], off offset:768
	global_load_dwordx4 v[214:217], v[182:183], off offset:768
	global_load_dwordx4 v[218:221], v[184:185], off offset:768
	global_load_dwordx4 v[230:233], v[66:67], off offset:768
	global_load_dwordx4 v[234:237], v[70:71], off offset:768
	s_waitcnt lgkmcnt(0)
	v_mfma_f32_32x32x16_bf16 v[18:33], v[210:213], v[226:229], v[18:33]
	global_load_dwordx4 v[210:213], v[68:69], off offset:768
	global_load_dwordx4 v[238:241], v[72:73], off offset:768
	s_setprio 1
	s_waitcnt vmcnt(7)
	ds_write_b128 v196, v[202:205]
	s_waitcnt vmcnt(6)
	ds_write_b128 v196, v[206:209] offset:4608
	s_waitcnt vmcnt(5)
	ds_write_b128 v196, v[214:217] offset:9216
	s_waitcnt vmcnt(4)
	ds_write_b128 v196, v[218:221] offset:13824
	s_waitcnt vmcnt(3)
	ds_write_b128 v196, v[230:233] offset:36864
	s_waitcnt vmcnt(2)
	ds_write_b128 v196, v[234:237] offset:41472
	s_waitcnt vmcnt(1)
	ds_write_b128 v196, v[210:213] offset:46080
	s_waitcnt vmcnt(0)
	ds_write_b128 v196, v[238:241] offset:50688
	v_mfma_f32_32x32x16_bf16 v[2:17], v[222:225], v[226:229], v[2:17]
	s_waitcnt lgkmcnt(0)
	s_barrier
	s_setprio 0
	ds_read_b128 v[202:205], v193
	ds_read_b128 v[206:209], v195 offset:36864
	ds_read_b128 v[210:213], v193 offset:32
	ds_read_b128 v[214:217], v195 offset:36896
	ds_read_b128 v[218:221], v193 offset:4608
	ds_read_b128 v[222:225], v193 offset:4640
	s_waitcnt lgkmcnt(4)
	v_mfma_f32_32x32x16_bf16 v[50:65], v[202:205], v[206:209], v[50:65]
	s_waitcnt lgkmcnt(1)
	v_mfma_f32_32x32x16_bf16 v[34:49], v[218:221], v[206:209], v[34:49]
	ds_read_b128 v[206:209], v195 offset:41472
	ds_read_b128 v[226:229], v195 offset:41504
	s_waitcnt lgkmcnt(1)
	v_mfma_f32_32x32x16_bf16 v[18:33], v[202:205], v[206:209], v[18:33]
	v_mfma_f32_32x32x16_bf16 v[2:17], v[218:221], v[206:209], v[2:17]
	v_mfma_f32_32x32x16_bf16 v[50:65], v[210:213], v[214:217], v[50:65]
	v_mfma_f32_32x32x16_bf16 v[34:49], v[222:225], v[214:217], v[34:49]
	s_waitcnt lgkmcnt(0)
	v_mfma_f32_32x32x16_bf16 v[18:33], v[210:213], v[226:229], v[18:33]
	ds_read_b128 v[202:205], v193 offset:64
	ds_read_b128 v[206:209], v195 offset:36928
	ds_read_b128 v[210:213], v193 offset:96
	ds_read_b128 v[214:217], v195 offset:36960
	v_mfma_f32_32x32x16_bf16 v[2:17], v[222:225], v[226:229], v[2:17]
	ds_read_b128 v[218:221], v193 offset:4672
	ds_read_b128 v[222:225], v193 offset:4704
	s_waitcnt lgkmcnt(4)
	v_mfma_f32_32x32x16_bf16 v[50:65], v[202:205], v[206:209], v[50:65]
	s_waitcnt lgkmcnt(1)
	v_mfma_f32_32x32x16_bf16 v[34:49], v[218:221], v[206:209], v[34:49]
	ds_read_b128 v[206:209], v195 offset:41536
	ds_read_b128 v[226:229], v195 offset:41568
	s_waitcnt lgkmcnt(1)
	v_mfma_f32_32x32x16_bf16 v[18:33], v[202:205], v[206:209], v[18:33]
	v_mfma_f32_32x32x16_bf16 v[2:17], v[218:221], v[206:209], v[2:17]
	v_mfma_f32_32x32x16_bf16 v[50:65], v[210:213], v[214:217], v[50:65]
	v_mfma_f32_32x32x16_bf16 v[34:49], v[222:225], v[214:217], v[34:49]
	global_load_dwordx4 v[202:205], v[178:179], off offset:896
	s_nop 0
	global_load_dwordx4 v[178:181], v[180:181], off offset:896
	s_nop 0
	global_load_dwordx4 v[206:209], v[182:183], off offset:896
	s_nop 0
	global_load_dwordx4 v[182:185], v[184:185], off offset:896
	s_nop 0
	global_load_dwordx4 v[214:217], v[66:67], off offset:896
	global_load_dwordx4 v[218:221], v[70:71], off offset:896
	s_nop 0
	global_load_dwordx4 v[66:69], v[68:69], off offset:896
	s_nop 0
	global_load_dwordx4 v[70:73], v[72:73], off offset:896
	s_setprio 1
	s_waitcnt vmcnt(7)
	ds_write_b128 v196, v[202:205] offset:18432
	s_waitcnt vmcnt(6)
	ds_write_b128 v196, v[178:181] offset:23040
	s_waitcnt vmcnt(5)
	ds_write_b128 v196, v[206:209] offset:27648
	s_waitcnt vmcnt(4)
	ds_write_b128 v196, v[182:185] offset:32256
	s_waitcnt vmcnt(3)
	ds_write_b128 v196, v[214:217] offset:55296
	s_waitcnt vmcnt(2)
	ds_write_b128 v196, v[218:221] offset:59904
	s_waitcnt vmcnt(1)
	ds_write_b128 v196, v[66:69] offset:64512
	s_waitcnt vmcnt(0)
	ds_write_b128 v197, v[70:73] offset:32256
	s_waitcnt lgkmcnt(8)
	v_mfma_f32_32x32x16_bf16 v[18:33], v[210:213], v[226:229], v[18:33]
	s_waitcnt lgkmcnt(0)
	s_barrier
	s_setprio 0
	ds_read_b128 v[66:69], v193 offset:18432
	ds_read_b128 v[70:73], v195 offset:55296
	ds_read_b128 v[178:181], v193 offset:18464
	ds_read_b128 v[182:185], v195 offset:55328
	ds_read_b128 v[202:205], v193 offset:23040
	ds_read_b128 v[206:209], v193 offset:23072
	v_mfma_f32_32x32x16_bf16 v[2:17], v[222:225], v[226:229], v[2:17]
	s_waitcnt lgkmcnt(4)
	v_mfma_f32_32x32x16_bf16 v[50:65], v[66:69], v[70:73], v[50:65]
	s_waitcnt lgkmcnt(1)
	v_mfma_f32_32x32x16_bf16 v[34:49], v[202:205], v[70:73], v[34:49]
	ds_read_b128 v[70:73], v195 offset:59904
	ds_read_b128 v[210:213], v195 offset:59936
	s_waitcnt lgkmcnt(1)
	v_mfma_f32_32x32x16_bf16 v[18:33], v[66:69], v[70:73], v[18:33]
	v_mfma_f32_32x32x16_bf16 v[2:17], v[202:205], v[70:73], v[2:17]
	v_mfma_f32_32x32x16_bf16 v[50:65], v[178:181], v[182:185], v[50:65]
	v_mfma_f32_32x32x16_bf16 v[34:49], v[206:209], v[182:185], v[34:49]
	s_waitcnt lgkmcnt(0)
	v_mfma_f32_32x32x16_bf16 v[18:33], v[178:181], v[210:213], v[18:33]
	ds_read_b128 v[66:69], v193 offset:18496
	ds_read_b128 v[70:73], v195 offset:55360
	ds_read_b128 v[178:181], v193 offset:18528
	ds_read_b128 v[182:185], v195 offset:55392
	v_mfma_f32_32x32x16_bf16 v[2:17], v[206:209], v[210:213], v[2:17]
	ds_read_b128 v[202:205], v193 offset:23104
	ds_read_b128 v[206:209], v193 offset:23136
	s_waitcnt lgkmcnt(4)
	v_mfma_f32_32x32x16_bf16 v[50:65], v[66:69], v[70:73], v[50:65]
	s_waitcnt lgkmcnt(1)
	v_mfma_f32_32x32x16_bf16 v[34:49], v[202:205], v[70:73], v[34:49]
	ds_read_b128 v[70:73], v195 offset:59968
	ds_read_b128 v[210:213], v195 offset:60000
	s_waitcnt lgkmcnt(0)
	s_barrier
	v_mfma_f32_32x32x16_bf16 v[18:33], v[66:69], v[70:73], v[18:33]
	v_mfma_f32_32x32x16_bf16 v[2:17], v[202:205], v[70:73], v[2:17]
	v_mfma_f32_32x32x16_bf16 v[50:65], v[178:181], v[182:185], v[50:65]
	v_mfma_f32_32x32x16_bf16 v[34:49], v[206:209], v[182:185], v[34:49]
	v_mfma_f32_32x32x16_bf16 v[18:33], v[178:181], v[210:213], v[18:33]
	v_mfma_f32_32x32x16_bf16 v[2:17], v[206:209], v[210:213], v[2:17]
	s_cbranch_scc1 .LBB0_902
	s_cmp_lg_u32 s17, 1
	s_mov_b64 s[4:5], -1
	s_cbranch_scc0 .LBB0_906
	s_mov_b64 s[4:5], 0

.Ldq1_p0_nores:
	v_sub_f32_e32 v250, v98, v151
	v_exp_f32_e32 v98, v250
	v_sub_f32_e32 v161, v99, v151
	v_exp_f32_e32 v99, v161
	v_sub_f32_e32 v250, v100, v151
	v_exp_f32_e32 v100, v250
	v_sub_f32_e32 v161, v101, v151
	v_exp_f32_e32 v101, v161
	v_sub_f32_e32 v250, v102, v151
	v_exp_f32_e32 v102, v250
	v_sub_f32_e32 v161, v103, v151
	v_exp_f32_e32 v103, v161
	v_sub_f32_e32 v250, v104, v151
	v_exp_f32_e32 v104, v250
	v_sub_f32_e32 v161, v105, v151
	v_exp_f32_e32 v105, v161
	v_add_f32_e32 v12, v12, v98
	v_add_f32_e32 v159, v159, v99
	v_add_f32_e32 v12, v12, v100
	v_add_f32_e32 v159, v159, v101
	v_add_f32_e32 v12, v12, v102
	v_add_f32_e32 v159, v159, v103
	v_add_f32_e32 v12, v12, v104
	v_add_f32_e32 v159, v159, v105
	v_cvt_pk_bf16_f32 v98, v98, v99
	v_cvt_pk_bf16_f32 v99, v100, v101
	v_cvt_pk_bf16_f32 v100, v102, v103
	v_cvt_pk_bf16_f32 v101, v104, v105
	ds_read_b128 v[14:17], v175 offset:34848
	s_waitcnt lgkmcnt(4)
	v_mfma_f32_32x32x16_bf16 v[66:81], v[208:211], v[98:101], v[66:81]
	v_sub_f32_e32 v250, v106, v151
	v_exp_f32_e32 v106, v250
	v_sub_f32_e32 v161, v107, v151
	v_exp_f32_e32 v107, v161
	v_sub_f32_e32 v250, v108, v151
	v_exp_f32_e32 v108, v250
	v_sub_f32_e32 v161, v109, v151
	v_exp_f32_e32 v109, v161
	ds_read_b128 v[208:211], v175 offset:39456
	s_waitcnt lgkmcnt(4)
	v_mfma_f32_32x32x16_bf16 v[50:65], v[252:255], v[98:101], v[50:65]
	v_sub_f32_e32 v250, v110, v151
	v_exp_f32_e32 v110, v250
	v_sub_f32_e32 v161, v111, v151
	v_exp_f32_e32 v111, v161
	v_sub_f32_e32 v250, v112, v151
	v_exp_f32_e32 v112, v250
	v_sub_f32_e32 v161, v113, v151
	v_exp_f32_e32 v113, v161
	ds_read_b128 v[252:255], v175 offset:44064
	s_waitcnt lgkmcnt(4)
	v_mfma_f32_32x32x16_bf16 v[34:49], v[4:7], v[98:101], v[34:49]
	v_add_f32_e32 v12, v12, v106
	v_add_f32_e32 v159, v159, v107
	v_add_f32_e32 v12, v12, v108
	v_add_f32_e32 v159, v159, v109
	v_add_f32_e32 v12, v12, v110
	v_add_f32_e32 v159, v159, v111
	v_add_f32_e32 v12, v12, v112
	v_add_f32_e32 v159, v159, v113
	ds_read_b128 v[4:7], v175 offset:48672
	s_waitcnt lgkmcnt(4)
	v_mfma_f32_32x32x16_bf16 v[18:33], v[8:11], v[98:101], v[18:33]
	v_cvt_pk_bf16_f32 v106, v106, v107
	v_cvt_pk_bf16_f32 v107, v108, v109
	v_cvt_pk_bf16_f32 v108, v110, v111
	v_cvt_pk_bf16_f32 v109, v112, v113
	ds_read_b128 v[8:11], v175 offset:34880
	s_waitcnt lgkmcnt(4)
	v_mfma_f32_32x32x16_bf16 v[66:81], v[14:17], v[106:109], v[66:81]
	v_sub_f32_e32 v250, v82, v151
	v_exp_f32_e32 v82, v250
	v_sub_f32_e32 v161, v83, v151
	v_exp_f32_e32 v83, v161
	v_sub_f32_e32 v250, v84, v151
	v_exp_f32_e32 v84, v250
	v_sub_f32_e32 v161, v85, v151
	v_exp_f32_e32 v85, v161
	ds_read_b128 v[14:17], v175 offset:39488
	s_waitcnt lgkmcnt(4)
	v_mfma_f32_32x32x16_bf16 v[50:65], v[208:211], v[106:109], v[50:65]
	v_sub_f32_e32 v250, v86, v151
	v_exp_f32_e32 v86, v250
	v_sub_f32_e32 v161, v87, v151
	v_exp_f32_e32 v87, v161
	v_sub_f32_e32 v250, v88, v151
	v_exp_f32_e32 v88, v250
	v_sub_f32_e32 v161, v89, v151
	v_exp_f32_e32 v89, v161
	ds_read_b128 v[208:211], v175 offset:44096
	s_waitcnt lgkmcnt(4)
	v_mfma_f32_32x32x16_bf16 v[34:49], v[252:255], v[106:109], v[34:49]
	v_add_f32_e32 v12, v12, v82
	v_add_f32_e32 v159, v159, v83
	v_add_f32_e32 v12, v12, v84
	v_add_f32_e32 v159, v159, v85
	v_add_f32_e32 v12, v12, v86
	v_add_f32_e32 v159, v159, v87
	v_add_f32_e32 v12, v12, v88
	v_add_f32_e32 v159, v159, v89
	ds_read_b128 v[252:255], v175 offset:48704
	s_waitcnt lgkmcnt(4)
	v_mfma_f32_32x32x16_bf16 v[18:33], v[4:7], v[106:109], v[18:33]
	v_cvt_pk_bf16_f32 v82, v82, v83
	v_cvt_pk_bf16_f32 v83, v84, v85
	v_cvt_pk_bf16_f32 v84, v86, v87
	v_cvt_pk_bf16_f32 v85, v88, v89
	ds_read_b128 v[4:7], v175 offset:34912
	s_waitcnt lgkmcnt(4)
	v_mfma_f32_32x32x16_bf16 v[66:81], v[8:11], v[82:85], v[66:81]
	v_sub_f32_e32 v250, v90, v151
	v_exp_f32_e32 v90, v250
	v_sub_f32_e32 v161, v91, v151
	v_exp_f32_e32 v91, v161
	v_sub_f32_e32 v250, v92, v151
	v_exp_f32_e32 v92, v250
	v_sub_f32_e32 v161, v93, v151
	v_exp_f32_e32 v93, v161
	ds_read_b128 v[8:11], v175 offset:39520
	s_waitcnt lgkmcnt(4)
	v_mfma_f32_32x32x16_bf16 v[50:65], v[14:17], v[82:85], v[50:65]
	v_sub_f32_e32 v250, v94, v151
	v_exp_f32_e32 v94, v250
	v_sub_f32_e32 v161, v95, v151
	v_exp_f32_e32 v95, v161
	v_sub_f32_e32 v250, v96, v151
	v_exp_f32_e32 v96, v250
	v_sub_f32_e32 v161, v97, v151
	v_exp_f32_e32 v97, v161
	s_setprio 1
	s_waitcnt vmcnt(7)
	ds_write_b128 v168, v[212:215] offset:17408
	s_waitcnt vmcnt(6)
	ds_write_b128 v170, v[216:219] offset:53248
	ds_read_b128 v[14:17], v175 offset:44128
	s_waitcnt lgkmcnt(6)
	v_mfma_f32_32x32x16_bf16 v[34:49], v[208:211], v[82:85], v[34:49]
	v_add_f32_e32 v12, v12, v90
	v_add_f32_e32 v159, v159, v91
	v_add_f32_e32 v12, v12, v92
	v_add_f32_e32 v159, v159, v93
	v_add_f32_e32 v12, v12, v94
	v_add_f32_e32 v159, v159, v95
	v_add_f32_e32 v12, v12, v96
	v_add_f32_e32 v159, v159, v97
	ds_read_b128 v[208:211], v175 offset:48736
	s_waitcnt lgkmcnt(6)
	v_mfma_f32_32x32x16_bf16 v[18:33], v[252:255], v[82:85], v[18:33]
	v_cvt_pk_bf16_f32 v90, v90, v91
	v_cvt_pk_bf16_f32 v91, v92, v93
	v_cvt_pk_bf16_f32 v92, v94, v95
	v_cvt_pk_bf16_f32 v93, v96, v97
	s_waitcnt vmcnt(5)
	ds_write_b128 v183, v[220:223] offset:17408
	s_waitcnt vmcnt(4)
	ds_write_b128 v188, v[224:227] offset:53248
	s_waitcnt lgkmcnt(7)
	v_mfma_f32_32x32x16_bf16 v[66:81], v[4:7], v[90:93], v[66:81]
	s_waitcnt vmcnt(3)
	ds_write_b128 v190, v[228:231] offset:17408
	s_waitcnt vmcnt(2)
	ds_write_b128 v193, v[232:235] offset:53248
	s_waitcnt lgkmcnt(8)
	v_mfma_f32_32x32x16_bf16 v[50:65], v[8:11], v[90:93], v[50:65]
	s_waitcnt lgkmcnt(5)
	v_mfma_f32_32x32x16_bf16 v[34:49], v[14:17], v[90:93], v[34:49]
	s_waitcnt vmcnt(1)
	ds_write_b128 v171, v[236:239] offset:17408
	s_waitcnt vmcnt(0)
	ds_write_b128 v173, v[240:243] offset:53248
	s_waitcnt lgkmcnt(6)
	v_mfma_f32_32x32x16_bf16 v[18:33], v[208:211], v[90:93], v[18:33]
	s_waitcnt lgkmcnt(0)
	s_barrier
	s_setprio 0
	s_cmp_eq_u32 s38, s41
	s_cbranch_scc1 .Ldq1_exit
	s_mov_b32 s42, s41

.Ldq1_p1_nores:
	v_sub_f32_e32 v250, v98, v151
	v_exp_f32_e32 v98, v250
	v_sub_f32_e32 v161, v99, v151
	v_exp_f32_e32 v99, v161
	v_sub_f32_e32 v250, v100, v151
	v_exp_f32_e32 v100, v250
	v_sub_f32_e32 v161, v101, v151
	v_exp_f32_e32 v101, v161
	v_sub_f32_e32 v250, v102, v151
	v_exp_f32_e32 v102, v250
	v_sub_f32_e32 v161, v103, v151
	v_exp_f32_e32 v103, v161
	v_sub_f32_e32 v250, v104, v151
	v_exp_f32_e32 v104, v250
	v_sub_f32_e32 v161, v105, v151
	v_exp_f32_e32 v105, v161
	v_add_f32_e32 v12, v12, v98
	v_add_f32_e32 v159, v159, v99
	v_add_f32_e32 v12, v12, v100
	v_add_f32_e32 v159, v159, v101
	v_add_f32_e32 v12, v12, v102
	v_add_f32_e32 v159, v159, v103
	v_add_f32_e32 v12, v12, v104
	v_add_f32_e32 v159, v159, v105
	v_cvt_pk_bf16_f32 v98, v98, v99
	v_cvt_pk_bf16_f32 v99, v100, v101
	v_cvt_pk_bf16_f32 v100, v102, v103
	v_cvt_pk_bf16_f32 v101, v104, v105
	ds_read_b128 v[14:17], v163 offset:34848
	s_waitcnt lgkmcnt(4)
	v_mfma_f32_32x32x16_bf16 v[66:81], v[208:211], v[98:101], v[66:81]
	v_sub_f32_e32 v250, v106, v151
	v_exp_f32_e32 v106, v250
	v_sub_f32_e32 v161, v107, v151
	v_exp_f32_e32 v107, v161
	v_sub_f32_e32 v250, v108, v151
	v_exp_f32_e32 v108, v250
	v_sub_f32_e32 v161, v109, v151
	v_exp_f32_e32 v109, v161
	ds_read_b128 v[208:211], v163 offset:39456
	s_waitcnt lgkmcnt(4)
	v_mfma_f32_32x32x16_bf16 v[50:65], v[252:255], v[98:101], v[50:65]
	v_sub_f32_e32 v250, v110, v151
	v_exp_f32_e32 v110, v250
	v_sub_f32_e32 v161, v111, v151
	v_exp_f32_e32 v111, v161
	v_sub_f32_e32 v250, v112, v151
	v_exp_f32_e32 v112, v250
	v_sub_f32_e32 v161, v113, v151
	v_exp_f32_e32 v113, v161
	ds_read_b128 v[252:255], v163 offset:44064
	s_waitcnt lgkmcnt(4)
	v_mfma_f32_32x32x16_bf16 v[34:49], v[4:7], v[98:101], v[34:49]
	v_add_f32_e32 v12, v12, v106
	v_add_f32_e32 v159, v159, v107
	v_add_f32_e32 v12, v12, v108
	v_add_f32_e32 v159, v159, v109
	v_add_f32_e32 v12, v12, v110
	v_add_f32_e32 v159, v159, v111
	v_add_f32_e32 v12, v12, v112
	v_add_f32_e32 v159, v159, v113
	ds_read_b128 v[4:7], v163 offset:48672
	s_waitcnt lgkmcnt(4)
	v_mfma_f32_32x32x16_bf16 v[18:33], v[8:11], v[98:101], v[18:33]
	v_cvt_pk_bf16_f32 v106, v106, v107
	v_cvt_pk_bf16_f32 v107, v108, v109
	v_cvt_pk_bf16_f32 v108, v110, v111
	v_cvt_pk_bf16_f32 v109, v112, v113
	ds_read_b128 v[8:11], v163 offset:34880
	s_waitcnt lgkmcnt(4)
	v_mfma_f32_32x32x16_bf16 v[66:81], v[14:17], v[106:109], v[66:81]
	v_sub_f32_e32 v250, v82, v151
	v_exp_f32_e32 v82, v250
	v_sub_f32_e32 v161, v83, v151
	v_exp_f32_e32 v83, v161
	v_sub_f32_e32 v250, v84, v151
	v_exp_f32_e32 v84, v250
	v_sub_f32_e32 v161, v85, v151
	v_exp_f32_e32 v85, v161
	ds_read_b128 v[14:17], v163 offset:39488
	s_waitcnt lgkmcnt(4)
	v_mfma_f32_32x32x16_bf16 v[50:65], v[208:211], v[106:109], v[50:65]
	v_sub_f32_e32 v250, v86, v151
	v_exp_f32_e32 v86, v250
	v_sub_f32_e32 v161, v87, v151
	v_exp_f32_e32 v87, v161
	v_sub_f32_e32 v250, v88, v151
	v_exp_f32_e32 v88, v250
	v_sub_f32_e32 v161, v89, v151
	v_exp_f32_e32 v89, v161
	ds_read_b128 v[208:211], v163 offset:44096
	s_waitcnt lgkmcnt(4)
	v_mfma_f32_32x32x16_bf16 v[34:49], v[252:255], v[106:109], v[34:49]
	v_add_f32_e32 v12, v12, v82
	v_add_f32_e32 v159, v159, v83
	v_add_f32_e32 v12, v12, v84
	v_add_f32_e32 v159, v159, v85
	v_add_f32_e32 v12, v12, v86
	v_add_f32_e32 v159, v159, v87
	v_add_f32_e32 v12, v12, v88
	v_add_f32_e32 v159, v159, v89
	ds_read_b128 v[252:255], v163 offset:48704
	s_waitcnt lgkmcnt(4)
	v_mfma_f32_32x32x16_bf16 v[18:33], v[4:7], v[106:109], v[18:33]
	v_cvt_pk_bf16_f32 v82, v82, v83
	v_cvt_pk_bf16_f32 v83, v84, v85
	v_cvt_pk_bf16_f32 v84, v86, v87
	v_cvt_pk_bf16_f32 v85, v88, v89
	ds_read_b128 v[4:7], v163 offset:34912
	s_waitcnt lgkmcnt(4)
	v_mfma_f32_32x32x16_bf16 v[66:81], v[8:11], v[82:85], v[66:81]
	v_sub_f32_e32 v250, v90, v151
	v_exp_f32_e32 v90, v250
	v_sub_f32_e32 v161, v91, v151
	v_exp_f32_e32 v91, v161
	v_sub_f32_e32 v250, v92, v151
	v_exp_f32_e32 v92, v250
	v_sub_f32_e32 v161, v93, v151
	v_exp_f32_e32 v93, v161
	ds_read_b128 v[8:11], v163 offset:39520
	s_waitcnt lgkmcnt(4)
	v_mfma_f32_32x32x16_bf16 v[50:65], v[14:17], v[82:85], v[50:65]
	v_sub_f32_e32 v250, v94, v151
	v_exp_f32_e32 v94, v250
	v_sub_f32_e32 v161, v95, v151
	v_exp_f32_e32 v95, v161
	v_sub_f32_e32 v250, v96, v151
	v_exp_f32_e32 v96, v250
	v_sub_f32_e32 v161, v97, v151
	v_exp_f32_e32 v97, v161
	s_setprio 1
	s_waitcnt vmcnt(7)
	ds_write_b128 v168, v[212:215]
	s_waitcnt vmcnt(6)
	ds_write_b128 v170, v[216:219] offset:34816
	ds_read_b128 v[14:17], v163 offset:44128
	s_waitcnt lgkmcnt(6)
	v_mfma_f32_32x32x16_bf16 v[34:49], v[208:211], v[82:85], v[34:49]
	v_add_f32_e32 v12, v12, v90
	v_add_f32_e32 v159, v159, v91
	v_add_f32_e32 v12, v12, v92
	v_add_f32_e32 v159, v159, v93
	v_add_f32_e32 v12, v12, v94
	v_add_f32_e32 v159, v159, v95
	v_add_f32_e32 v12, v12, v96
	v_add_f32_e32 v159, v159, v97
	ds_read_b128 v[208:211], v163 offset:48736
	s_waitcnt lgkmcnt(6)
	v_mfma_f32_32x32x16_bf16 v[18:33], v[252:255], v[82:85], v[18:33]
	v_cvt_pk_bf16_f32 v90, v90, v91
	v_cvt_pk_bf16_f32 v91, v92, v93
	v_cvt_pk_bf16_f32 v92, v94, v95
	v_cvt_pk_bf16_f32 v93, v96, v97
	s_waitcnt vmcnt(5)
	ds_write_b128 v183, v[220:223]
	s_waitcnt vmcnt(4)
	ds_write_b128 v188, v[224:227] offset:34816
	s_waitcnt lgkmcnt(7)
	v_mfma_f32_32x32x16_bf16 v[66:81], v[4:7], v[90:93], v[66:81]
	s_waitcnt vmcnt(3)
	ds_write_b128 v190, v[228:231]
	s_waitcnt vmcnt(2)
	ds_write_b128 v193, v[232:235] offset:34816
	s_waitcnt lgkmcnt(8)
	v_mfma_f32_32x32x16_bf16 v[50:65], v[8:11], v[90:93], v[50:65]
	s_waitcnt lgkmcnt(5)
	v_mfma_f32_32x32x16_bf16 v[34:49], v[14:17], v[90:93], v[34:49]
	s_waitcnt vmcnt(1)
	ds_write_b128 v171, v[236:239]
	s_waitcnt vmcnt(0)
	ds_write_b128 v173, v[240:243] offset:34816
	s_waitcnt lgkmcnt(6)
	v_mfma_f32_32x32x16_bf16 v[18:33], v[208:211], v[90:93], v[18:33]
	s_waitcnt lgkmcnt(0)
	s_barrier
	s_setprio 0
	s_cmp_eq_u32 s38, s41
	s_cbranch_scc1 .Ldq1_exit
	s_mov_b32 s42, s41
	s_branch .Ldq1_p0_top

.LBB0_1795:
	s_cmp_eq_u32 s2, 0x100000
	s_cselect_b32 s0, s13, 0x5400000
	s_cmp_lg_u32 s2, 0
	v_lshl_add_u64 v[2:3], v[148:149], 0, s[2:3]
	s_cselect_b32 s0, s0, 0
	v_add_co_u32_e32 v174, vcc, s14, v2
	s_add_u32 s4, s82, s0
	v_lshl_add_u64 v[4:5], v[152:153], 0, s[2:3]
	v_addc_co_u32_e32 v175, vcc, 0, v3, vcc
	s_addc_u32 s5, s83, 0
	v_add_co_u32_e32 v176, vcc, s14, v4
	v_lshl_add_u64 v[10:11], v[154:155], 0, s[2:3]
	v_lshl_add_u64 v[6:7], s[4:5], 0, v[104:105]
	v_addc_co_u32_e32 v177, vcc, 0, v5, vcc
	v_lshl_add_u64 v[66:67], v[6:7], 0, v[82:83]
	v_lshl_add_u64 v[6:7], s[4:5], 0, v[112:113]
	v_add_co_u32_e32 v178, vcc, s14, v10
	v_lshl_add_u64 v[12:13], v[156:157], 0, s[2:3]
	v_lshl_add_u64 v[70:71], v[6:7], 0, v[82:83]
	v_lshl_add_u64 v[6:7], s[4:5], 0, v[116:117]
	v_addc_co_u32_e32 v179, vcc, 0, v11, vcc
	v_lshl_add_u64 v[68:69], v[6:7], 0, v[82:83]
	v_lshl_add_u64 v[6:7], s[4:5], 0, v[120:121]
	v_add_co_u32_e32 v180, vcc, s14, v12
	v_lshl_add_u64 v[72:73], v[6:7], 0, v[82:83]
	global_load_dwordx4 v[2:5], v[174:175], off
	global_load_dwordx4 v[6:9], v[176:177], off
	v_addc_co_u32_e32 v181, vcc, 0, v13, vcc
	global_load_dwordx4 v[10:13], v[178:179], off
	global_load_dwordx4 v[14:17], v[180:181], off
	global_load_dwordx4 v[18:21], v[66:67], off
	global_load_dwordx4 v[22:25], v[70:71], off
	global_load_dwordx4 v[26:29], v[68:69], off
	global_load_dwordx4 v[30:33], v[72:73], off
	s_cmp_lt_i32 s17, 1
	s_mov_b32 s0, s11
	s_waitcnt vmcnt(7)
	ds_write_b128 v189, v[2:5]
	s_waitcnt vmcnt(6)
	ds_write_b128 v189, v[6:9] offset:4608
	s_waitcnt vmcnt(5)
	ds_write_b128 v189, v[10:13] offset:9216
	s_waitcnt vmcnt(4)
	ds_write_b128 v189, v[14:17] offset:13824
	s_waitcnt vmcnt(3)
	ds_write_b128 v189, v[18:21] offset:36864
	s_waitcnt vmcnt(2)
	ds_write_b128 v189, v[22:25] offset:41472
	s_waitcnt vmcnt(1)
	ds_write_b128 v189, v[26:29] offset:46080
	s_waitcnt vmcnt(0)
	ds_write_b128 v189, v[30:33] offset:50688
	s_waitcnt lgkmcnt(0)
	s_barrier
	ds_read_b128 v[2:5], v186
	ds_read_b128 v[6:9], v188 offset:36864
	ds_read_b128 v[196:199], v186 offset:32
	ds_read_b128 v[200:203], v188 offset:36896
	ds_read_b128 v[10:13], v186 offset:4608
	ds_read_b128 v[204:207], v186 offset:4640
	s_waitcnt lgkmcnt(4)
	v_mfma_f32_32x32x16_bf16 v[50:65], v[2:5], v[6:9], 0
	s_waitcnt lgkmcnt(1)
	v_mfma_f32_32x32x16_bf16 v[34:49], v[10:13], v[6:9], 0
	ds_read_b128 v[6:9], v188 offset:41472
	ds_read_b128 v[208:211], v188 offset:41504
	s_waitcnt lgkmcnt(1)
	v_mfma_f32_32x32x16_bf16 v[18:33], v[2:5], v[6:9], 0
	v_mfma_f32_32x32x16_bf16 v[2:17], v[10:13], v[6:9], 0
	v_mfma_f32_32x32x16_bf16 v[50:65], v[196:199], v[200:203], v[50:65]
	v_mfma_f32_32x32x16_bf16 v[34:49], v[204:207], v[200:203], v[34:49]
	s_waitcnt lgkmcnt(0)
	v_mfma_f32_32x32x16_bf16 v[18:33], v[196:199], v[208:211], v[18:33]
	v_mfma_f32_32x32x16_bf16 v[2:17], v[204:207], v[208:211], v[2:17]
	ds_read_b128 v[196:199], v186 offset:64
	ds_read_b128 v[200:203], v188 offset:36928
	ds_read_b128 v[204:207], v186 offset:96
	ds_read_b128 v[208:211], v188 offset:36960
	ds_read_b128 v[212:215], v186 offset:4672
	ds_read_b128 v[216:219], v186 offset:4704
	s_waitcnt lgkmcnt(4)
	v_mfma_f32_32x32x16_bf16 v[50:65], v[196:199], v[200:203], v[50:65]
	s_waitcnt lgkmcnt(1)
	v_mfma_f32_32x32x16_bf16 v[34:49], v[212:215], v[200:203], v[34:49]
	ds_read_b128 v[200:203], v188 offset:41536
	ds_read_b128 v[220:223], v188 offset:41568
	s_waitcnt lgkmcnt(1)
	v_mfma_f32_32x32x16_bf16 v[18:33], v[196:199], v[200:203], v[18:33]
	v_mfma_f32_32x32x16_bf16 v[2:17], v[212:215], v[200:203], v[2:17]
	v_mfma_f32_32x32x16_bf16 v[50:65], v[204:207], v[208:211], v[50:65]
	v_mfma_f32_32x32x16_bf16 v[34:49], v[216:219], v[208:211], v[34:49]
	global_load_dwordx4 v[196:199], v[174:175], off offset:128
	global_load_dwordx4 v[200:203], v[176:177], off offset:128
	global_load_dwordx4 v[208:211], v[178:179], off offset:128
	global_load_dwordx4 v[212:215], v[180:181], off offset:128
	global_load_dwordx4 v[224:227], v[66:67], off offset:128
	global_load_dwordx4 v[228:231], v[70:71], off offset:128
	s_waitcnt lgkmcnt(0)
	v_mfma_f32_32x32x16_bf16 v[18:33], v[204:207], v[220:223], v[18:33]
	global_load_dwordx4 v[204:207], v[68:69], off offset:128
	global_load_dwordx4 v[232:235], v[72:73], off offset:128
	s_setprio 1
	s_waitcnt vmcnt(7)
	ds_write_b128 v189, v[196:199] offset:18432
	s_waitcnt vmcnt(6)
	ds_write_b128 v189, v[200:203] offset:23040
	s_waitcnt vmcnt(5)
	ds_write_b128 v189, v[208:211] offset:27648
	s_waitcnt vmcnt(4)
	ds_write_b128 v189, v[212:215] offset:32256
	s_waitcnt vmcnt(3)
	ds_write_b128 v189, v[224:227] offset:55296
	s_waitcnt vmcnt(2)
	ds_write_b128 v189, v[228:231] offset:59904
	s_waitcnt vmcnt(1)
	ds_write_b128 v189, v[204:207] offset:64512
	s_waitcnt vmcnt(0)
	ds_write_b128 v190, v[232:235] offset:32256
	v_mfma_f32_32x32x16_bf16 v[2:17], v[216:219], v[220:223], v[2:17]
	s_waitcnt lgkmcnt(0)
	s_barrier
	s_setprio 0
	ds_read_b128 v[196:199], v186 offset:18432
	ds_read_b128 v[200:203], v188 offset:55296
	ds_read_b128 v[204:207], v186 offset:18464
	ds_read_b128 v[208:211], v188 offset:55328
	ds_read_b128 v[212:215], v186 offset:23040
	ds_read_b128 v[216:219], v186 offset:23072
	s_waitcnt lgkmcnt(4)
	v_mfma_f32_32x32x16_bf16 v[50:65], v[196:199], v[200:203], v[50:65]
	s_waitcnt lgkmcnt(1)
	v_mfma_f32_32x32x16_bf16 v[34:49], v[212:215], v[200:203], v[34:49]
	ds_read_b128 v[200:203], v188 offset:59904
	ds_read_b128 v[220:223], v188 offset:59936
	s_waitcnt lgkmcnt(1)
	v_mfma_f32_32x32x16_bf16 v[18:33], v[196:199], v[200:203], v[18:33]
	v_mfma_f32_32x32x16_bf16 v[2:17], v[212:215], v[200:203], v[2:17]
	v_mfma_f32_32x32x16_bf16 v[50:65], v[204:207], v[208:211], v[50:65]
	v_mfma_f32_32x32x16_bf16 v[34:49], v[216:219], v[208:211], v[34:49]
	s_waitcnt lgkmcnt(0)
	v_mfma_f32_32x32x16_bf16 v[18:33], v[204:207], v[220:223], v[18:33]
	ds_read_b128 v[196:199], v186 offset:18496
	ds_read_b128 v[200:203], v188 offset:55360
	ds_read_b128 v[204:207], v186 offset:18528
	ds_read_b128 v[208:211], v188 offset:55392
	v_mfma_f32_32x32x16_bf16 v[2:17], v[216:219], v[220:223], v[2:17]
	ds_read_b128 v[212:215], v186 offset:23104
	ds_read_b128 v[216:219], v186 offset:23136
	s_waitcnt lgkmcnt(4)
	v_mfma_f32_32x32x16_bf16 v[50:65], v[196:199], v[200:203], v[50:65]
	s_waitcnt lgkmcnt(1)
	v_mfma_f32_32x32x16_bf16 v[34:49], v[212:215], v[200:203], v[34:49]
	ds_read_b128 v[200:203], v188 offset:59968
	ds_read_b128 v[220:223], v188 offset:60000
	s_waitcnt lgkmcnt(1)
	v_mfma_f32_32x32x16_bf16 v[18:33], v[196:199], v[200:203], v[18:33]
	v_mfma_f32_32x32x16_bf16 v[2:17], v[212:215], v[200:203], v[2:17]
	v_mfma_f32_32x32x16_bf16 v[50:65], v[204:207], v[208:211], v[50:65]
	v_mfma_f32_32x32x16_bf16 v[34:49], v[216:219], v[208:211], v[34:49]
	global_load_dwordx4 v[196:199], v[174:175], off offset:256
	global_load_dwordx4 v[200:203], v[176:177], off offset:256
	global_load_dwordx4 v[208:211], v[178:179], off offset:256
	global_load_dwordx4 v[212:215], v[180:181], off offset:256
	global_load_dwordx4 v[224:227], v[66:67], off offset:256
	global_load_dwordx4 v[228:231], v[70:71], off offset:256
	s_waitcnt lgkmcnt(0)
	v_mfma_f32_32x32x16_bf16 v[18:33], v[204:207], v[220:223], v[18:33]
	global_load_dwordx4 v[204:207], v[68:69], off offset:256
	global_load_dwordx4 v[232:235], v[72:73], off offset:256
	s_setprio 1
	s_waitcnt vmcnt(7)
	ds_write_b128 v189, v[196:199]
	s_waitcnt vmcnt(6)
	ds_write_b128 v189, v[200:203] offset:4608
	s_waitcnt vmcnt(5)
	ds_write_b128 v189, v[208:211] offset:9216
	s_waitcnt vmcnt(4)
	ds_write_b128 v189, v[212:215] offset:13824
	s_waitcnt vmcnt(3)
	ds_write_b128 v189, v[224:227] offset:36864
	s_waitcnt vmcnt(2)
	ds_write_b128 v189, v[228:231] offset:41472
	s_waitcnt vmcnt(1)
	ds_write_b128 v189, v[204:207] offset:46080
	s_waitcnt vmcnt(0)
	ds_write_b128 v189, v[232:235] offset:50688
	v_mfma_f32_32x32x16_bf16 v[2:17], v[216:219], v[220:223], v[2:17]
	s_waitcnt lgkmcnt(0)
	s_barrier
	s_setprio 0
	ds_read_b128 v[196:199], v186
	ds_read_b128 v[200:203], v188 offset:36864
	ds_read_b128 v[204:207], v186 offset:32
	ds_read_b128 v[208:211], v188 offset:36896
	ds_read_b128 v[212:215], v186 offset:4608
	ds_read_b128 v[216:219], v186 offset:4640
	s_waitcnt lgkmcnt(4)
	v_mfma_f32_32x32x16_bf16 v[50:65], v[196:199], v[200:203], v[50:65]
	s_waitcnt lgkmcnt(1)
	v_mfma_f32_32x32x16_bf16 v[34:49], v[212:215], v[200:203], v[34:49]
	ds_read_b128 v[200:203], v188 offset:41472
	ds_read_b128 v[220:223], v188 offset:41504
	s_waitcnt lgkmcnt(1)
	v_mfma_f32_32x32x16_bf16 v[18:33], v[196:199], v[200:203], v[18:33]
	v_mfma_f32_32x32x16_bf16 v[2:17], v[212:215], v[200:203], v[2:17]
	v_mfma_f32_32x32x16_bf16 v[50:65], v[204:207], v[208:211], v[50:65]
	v_mfma_f32_32x32x16_bf16 v[34:49], v[216:219], v[208:211], v[34:49]
	s_waitcnt lgkmcnt(0)
	v_mfma_f32_32x32x16_bf16 v[18:33], v[204:207], v[220:223], v[18:33]
	ds_read_b128 v[196:199], v186 offset:64
	ds_read_b128 v[200:203], v188 offset:36928
	ds_read_b128 v[204:207], v186 offset:96
	ds_read_b128 v[208:211], v188 offset:36960
	v_mfma_f32_32x32x16_bf16 v[2:17], v[216:219], v[220:223], v[2:17]
	ds_read_b128 v[212:215], v186 offset:4672
	ds_read_b128 v[216:219], v186 offset:4704
	s_waitcnt lgkmcnt(4)
	v_mfma_f32_32x32x16_bf16 v[50:65], v[196:199], v[200:203], v[50:65]
	s_waitcnt lgkmcnt(1)
	v_mfma_f32_32x32x16_bf16 v[34:49], v[212:215], v[200:203], v[34:49]
	ds_read_b128 v[200:203], v188 offset:41536
	ds_read_b128 v[220:223], v188 offset:41568
	s_waitcnt lgkmcnt(1)
	v_mfma_f32_32x32x16_bf16 v[18:33], v[196:199], v[200:203], v[18:33]
	v_mfma_f32_32x32x16_bf16 v[2:17], v[212:215], v[200:203], v[2:17]
	v_mfma_f32_32x32x16_bf16 v[50:65], v[204:207], v[208:211], v[50:65]
	v_mfma_f32_32x32x16_bf16 v[34:49], v[216:219], v[208:211], v[34:49]
	global_load_dwordx4 v[196:199], v[174:175], off offset:384
	global_load_dwordx4 v[200:203], v[176:177], off offset:384
	global_load_dwordx4 v[208:211], v[178:179], off offset:384
	global_load_dwordx4 v[212:215], v[180:181], off offset:384
	global_load_dwordx4 v[224:227], v[66:67], off offset:384
	global_load_dwordx4 v[228:231], v[70:71], off offset:384
	s_waitcnt lgkmcnt(0)
	v_mfma_f32_32x32x16_bf16 v[18:33], v[204:207], v[220:223], v[18:33]
	global_load_dwordx4 v[204:207], v[68:69], off offset:384
	global_load_dwordx4 v[232:235], v[72:73], off offset:384
	s_setprio 1
	s_waitcnt vmcnt(7)
	ds_write_b128 v189, v[196:199] offset:18432
	s_waitcnt vmcnt(6)
	ds_write_b128 v189, v[200:203] offset:23040
	s_waitcnt vmcnt(5)
	ds_write_b128 v189, v[208:211] offset:27648
	s_waitcnt vmcnt(4)
	ds_write_b128 v189, v[212:215] offset:32256
	s_waitcnt vmcnt(3)
	ds_write_b128 v189, v[224:227] offset:55296
	s_waitcnt vmcnt(2)
	ds_write_b128 v189, v[228:231] offset:59904
	s_waitcnt vmcnt(1)
	ds_write_b128 v189, v[204:207] offset:64512
	s_waitcnt vmcnt(0)
	ds_write_b128 v190, v[232:235] offset:32256
	v_mfma_f32_32x32x16_bf16 v[2:17], v[216:219], v[220:223], v[2:17]
	s_waitcnt lgkmcnt(0)
	s_barrier
	s_setprio 0
	ds_read_b128 v[196:199], v186 offset:18432
	ds_read_b128 v[200:203], v188 offset:55296
	ds_read_b128 v[204:207], v186 offset:18464
	ds_read_b128 v[208:211], v188 offset:55328
	ds_read_b128 v[212:215], v186 offset:23040
	ds_read_b128 v[216:219], v186 offset:23072
	s_waitcnt lgkmcnt(4)
	v_mfma_f32_32x32x16_bf16 v[50:65], v[196:199], v[200:203], v[50:65]
	s_waitcnt lgkmcnt(1)
	v_mfma_f32_32x32x16_bf16 v[34:49], v[212:215], v[200:203], v[34:49]
	ds_read_b128 v[200:203], v188 offset:59904
	ds_read_b128 v[220:223], v188 offset:59936
	s_waitcnt lgkmcnt(1)
	v_mfma_f32_32x32x16_bf16 v[18:33], v[196:199], v[200:203], v[18:33]
	v_mfma_f32_32x32x16_bf16 v[2:17], v[212:215], v[200:203], v[2:17]
	v_mfma_f32_32x32x16_bf16 v[50:65], v[204:207], v[208:211], v[50:65]
	v_mfma_f32_32x32x16_bf16 v[34:49], v[216:219], v[208:211], v[34:49]
	s_waitcnt lgkmcnt(0)
	v_mfma_f32_32x32x16_bf16 v[18:33], v[204:207], v[220:223], v[18:33]
	ds_read_b128 v[196:199], v186 offset:18496
	ds_read_b128 v[200:203], v188 offset:55360
	ds_read_b128 v[204:207], v186 offset:18528
	ds_read_b128 v[208:211], v188 offset:55392
	v_mfma_f32_32x32x16_bf16 v[2:17], v[216:219], v[220:223], v[2:17]
	ds_read_b128 v[212:215], v186 offset:23104
	ds_read_b128 v[216:219], v186 offset:23136
	s_waitcnt lgkmcnt(4)
	v_mfma_f32_32x32x16_bf16 v[50:65], v[196:199], v[200:203], v[50:65]
	s_waitcnt lgkmcnt(1)
	v_mfma_f32_32x32x16_bf16 v[34:49], v[212:215], v[200:203], v[34:49]
	ds_read_b128 v[200:203], v188 offset:59968
	ds_read_b128 v[220:223], v188 offset:60000
	s_waitcnt lgkmcnt(1)
	v_mfma_f32_32x32x16_bf16 v[18:33], v[196:199], v[200:203], v[18:33]
	v_mfma_f32_32x32x16_bf16 v[2:17], v[212:215], v[200:203], v[2:17]
	v_mfma_f32_32x32x16_bf16 v[50:65], v[204:207], v[208:211], v[50:65]
	v_mfma_f32_32x32x16_bf16 v[34:49], v[216:219], v[208:211], v[34:49]
	global_load_dwordx4 v[196:199], v[174:175], off offset:512
	global_load_dwordx4 v[200:203], v[176:177], off offset:512
	global_load_dwordx4 v[208:211], v[178:179], off offset:512
	global_load_dwordx4 v[212:215], v[180:181], off offset:512
	global_load_dwordx4 v[224:227], v[66:67], off offset:512
	global_load_dwordx4 v[228:231], v[70:71], off offset:512
	s_waitcnt lgkmcnt(0)
	v_mfma_f32_32x32x16_bf16 v[18:33], v[204:207], v[220:223], v[18:33]
	global_load_dwordx4 v[204:207], v[68:69], off offset:512
	global_load_dwordx4 v[232:235], v[72:73], off offset:512
	s_setprio 1
	s_waitcnt vmcnt(7)
	ds_write_b128 v189, v[196:199]
	s_waitcnt vmcnt(6)
	ds_write_b128 v189, v[200:203] offset:4608
	s_waitcnt vmcnt(5)
	ds_write_b128 v189, v[208:211] offset:9216
	s_waitcnt vmcnt(4)
	ds_write_b128 v189, v[212:215] offset:13824
	s_waitcnt vmcnt(3)
	ds_write_b128 v189, v[224:227] offset:36864
	s_waitcnt vmcnt(2)
	ds_write_b128 v189, v[228:231] offset:41472
	s_waitcnt vmcnt(1)
	ds_write_b128 v189, v[204:207] offset:46080
	s_waitcnt vmcnt(0)
	ds_write_b128 v189, v[232:235] offset:50688
	v_mfma_f32_32x32x16_bf16 v[2:17], v[216:219], v[220:223], v[2:17]
	s_waitcnt lgkmcnt(0)
	s_barrier
	s_setprio 0
	ds_read_b128 v[196:199], v186
	ds_read_b128 v[200:203], v188 offset:36864
	ds_read_b128 v[204:207], v186 offset:32
	ds_read_b128 v[208:211], v188 offset:36896
	ds_read_b128 v[212:215], v186 offset:4608
	ds_read_b128 v[216:219], v186 offset:4640
	s_waitcnt lgkmcnt(4)
	v_mfma_f32_32x32x16_bf16 v[50:65], v[196:199], v[200:203], v[50:65]
	s_waitcnt lgkmcnt(1)
	v_mfma_f32_32x32x16_bf16 v[34:49], v[212:215], v[200:203], v[34:49]
	ds_read_b128 v[200:203], v188 offset:41472
	ds_read_b128 v[220:223], v188 offset:41504
	s_waitcnt lgkmcnt(1)
	v_mfma_f32_32x32x16_bf16 v[18:33], v[196:199], v[200:203], v[18:33]
	v_mfma_f32_32x32x16_bf16 v[2:17], v[212:215], v[200:203], v[2:17]
	v_mfma_f32_32x32x16_bf16 v[50:65], v[204:207], v[208:211], v[50:65]
	v_mfma_f32_32x32x16_bf16 v[34:49], v[216:219], v[208:211], v[34:49]
	s_waitcnt lgkmcnt(0)
	v_mfma_f32_32x32x16_bf16 v[18:33], v[204:207], v[220:223], v[18:33]
	ds_read_b128 v[196:199], v186 offset:64
	ds_read_b128 v[200:203], v188 offset:36928
	ds_read_b128 v[204:207], v186 offset:96
	ds_read_b128 v[208:211], v188 offset:36960
	v_mfma_f32_32x32x16_bf16 v[2:17], v[216:219], v[220:223], v[2:17]
	ds_read_b128 v[212:215], v186 offset:4672
	ds_read_b128 v[216:219], v186 offset:4704
	s_waitcnt lgkmcnt(4)
	v_mfma_f32_32x32x16_bf16 v[50:65], v[196:199], v[200:203], v[50:65]
	s_waitcnt lgkmcnt(1)
	v_mfma_f32_32x32x16_bf16 v[34:49], v[212:215], v[200:203], v[34:49]
	ds_read_b128 v[200:203], v188 offset:41536
	ds_read_b128 v[220:223], v188 offset:41568
	s_waitcnt lgkmcnt(1)
	v_mfma_f32_32x32x16_bf16 v[18:33], v[196:199], v[200:203], v[18:33]
	v_mfma_f32_32x32x16_bf16 v[2:17], v[212:215], v[200:203], v[2:17]
	v_mfma_f32_32x32x16_bf16 v[50:65], v[204:207], v[208:211], v[50:65]
	v_mfma_f32_32x32x16_bf16 v[34:49], v[216:219], v[208:211], v[34:49]
	global_load_dwordx4 v[196:199], v[174:175], off offset:640
	global_load_dwordx4 v[200:203], v[176:177], off offset:640
	global_load_dwordx4 v[208:211], v[178:179], off offset:640
	global_load_dwordx4 v[212:215], v[180:181], off offset:640
	global_load_dwordx4 v[224:227], v[66:67], off offset:640
	global_load_dwordx4 v[228:231], v[70:71], off offset:640
	s_waitcnt lgkmcnt(0)
	v_mfma_f32_32x32x16_bf16 v[18:33], v[204:207], v[220:223], v[18:33]
	global_load_dwordx4 v[204:207], v[68:69], off offset:640
	global_load_dwordx4 v[232:235], v[72:73], off offset:640
	s_setprio 1
	s_waitcnt vmcnt(7)
	ds_write_b128 v189, v[196:199] offset:18432
	s_waitcnt vmcnt(6)
	ds_write_b128 v189, v[200:203] offset:23040
	s_waitcnt vmcnt(5)
	ds_write_b128 v189, v[208:211] offset:27648
	s_waitcnt vmcnt(4)
	ds_write_b128 v189, v[212:215] offset:32256
	s_waitcnt vmcnt(3)
	ds_write_b128 v189, v[224:227] offset:55296
	s_waitcnt vmcnt(2)
	ds_write_b128 v189, v[228:231] offset:59904
	s_waitcnt vmcnt(1)
	ds_write_b128 v189, v[204:207] offset:64512
	s_waitcnt vmcnt(0)
	ds_write_b128 v190, v[232:235] offset:32256
	v_mfma_f32_32x32x16_bf16 v[2:17], v[216:219], v[220:223], v[2:17]
	s_waitcnt lgkmcnt(0)
	s_barrier
	s_setprio 0
	ds_read_b128 v[196:199], v186 offset:18432
	ds_read_b128 v[200:203], v188 offset:55296
	ds_read_b128 v[204:207], v186 offset:18464
	ds_read_b128 v[208:211], v188 offset:55328
	ds_read_b128 v[212:215], v186 offset:23040
	ds_read_b128 v[216:219], v186 offset:23072
	s_waitcnt lgkmcnt(4)
	v_mfma_f32_32x32x16_bf16 v[50:65], v[196:199], v[200:203], v[50:65]
	s_waitcnt lgkmcnt(1)
	v_mfma_f32_32x32x16_bf16 v[34:49], v[212:215], v[200:203], v[34:49]
	ds_read_b128 v[200:203], v188 offset:59904
	ds_read_b128 v[220:223], v188 offset:59936
	s_waitcnt lgkmcnt(1)
	v_mfma_f32_32x32x16_bf16 v[18:33], v[196:199], v[200:203], v[18:33]
	v_mfma_f32_32x32x16_bf16 v[2:17], v[212:215], v[200:203], v[2:17]
	v_mfma_f32_32x32x16_bf16 v[50:65], v[204:207], v[208:211], v[50:65]
	v_mfma_f32_32x32x16_bf16 v[34:49], v[216:219], v[208:211], v[34:49]
	s_waitcnt lgkmcnt(0)
	v_mfma_f32_32x32x16_bf16 v[18:33], v[204:207], v[220:223], v[18:33]
	ds_read_b128 v[196:199], v186 offset:18496
	ds_read_b128 v[200:203], v188 offset:55360
	ds_read_b128 v[204:207], v186 offset:18528
	ds_read_b128 v[208:211], v188 offset:55392
	v_mfma_f32_32x32x16_bf16 v[2:17], v[216:219], v[220:223], v[2:17]
	ds_read_b128 v[212:215], v186 offset:23104
	ds_read_b128 v[216:219], v186 offset:23136
	s_waitcnt lgkmcnt(4)
	v_mfma_f32_32x32x16_bf16 v[50:65], v[196:199], v[200:203], v[50:65]
	s_waitcnt lgkmcnt(1)
	v_mfma_f32_32x32x16_bf16 v[34:49], v[212:215], v[200:203], v[34:49]
	ds_read_b128 v[200:203], v188 offset:59968
	ds_read_b128 v[220:223], v188 offset:60000
	s_waitcnt lgkmcnt(1)
	v_mfma_f32_32x32x16_bf16 v[18:33], v[196:199], v[200:203], v[18:33]
	v_mfma_f32_32x32x16_bf16 v[2:17], v[212:215], v[200:203], v[2:17]
	v_mfma_f32_32x32x16_bf16 v[50:65], v[204:207], v[208:211], v[50:65]
	v_mfma_f32_32x32x16_bf16 v[34:49], v[216:219], v[208:211], v[34:49]
	global_load_dwordx4 v[196:199], v[174:175], off offset:768
	global_load_dwordx4 v[200:203], v[176:177], off offset:768
	global_load_dwordx4 v[208:211], v[178:179], off offset:768
	global_load_dwordx4 v[212:215], v[180:181], off offset:768
	global_load_dwordx4 v[224:227], v[66:67], off offset:768
	global_load_dwordx4 v[228:231], v[70:71], off offset:768
	s_waitcnt lgkmcnt(0)
	v_mfma_f32_32x32x16_bf16 v[18:33], v[204:207], v[220:223], v[18:33]
	global_load_dwordx4 v[204:207], v[68:69], off offset:768
	global_load_dwordx4 v[232:235], v[72:73], off offset:768
	s_setprio 1
	s_waitcnt vmcnt(7)
	ds_write_b128 v189, v[196:199]
	s_waitcnt vmcnt(6)
	ds_write_b128 v189, v[200:203] offset:4608
	s_waitcnt vmcnt(5)
	ds_write_b128 v189, v[208:211] offset:9216
	s_waitcnt vmcnt(4)
	ds_write_b128 v189, v[212:215] offset:13824
	s_waitcnt vmcnt(3)
	ds_write_b128 v189, v[224:227] offset:36864
	s_waitcnt vmcnt(2)
	ds_write_b128 v189, v[228:231] offset:41472
	s_waitcnt vmcnt(1)
	ds_write_b128 v189, v[204:207] offset:46080
	s_waitcnt vmcnt(0)
	ds_write_b128 v189, v[232:235] offset:50688
	v_mfma_f32_32x32x16_bf16 v[2:17], v[216:219], v[220:223], v[2:17]
	s_waitcnt lgkmcnt(0)
	s_barrier
	s_setprio 0
	ds_read_b128 v[196:199], v186
	ds_read_b128 v[200:203], v188 offset:36864
	ds_read_b128 v[204:207], v186 offset:32
	ds_read_b128 v[208:211], v188 offset:36896
	ds_read_b128 v[212:215], v186 offset:4608
	ds_read_b128 v[216:219], v186 offset:4640
	s_waitcnt lgkmcnt(4)
	v_mfma_f32_32x32x16_bf16 v[50:65], v[196:199], v[200:203], v[50:65]
	s_waitcnt lgkmcnt(1)
	v_mfma_f32_32x32x16_bf16 v[34:49], v[212:215], v[200:203], v[34:49]
	ds_read_b128 v[200:203], v188 offset:41472
	ds_read_b128 v[220:223], v188 offset:41504
	s_waitcnt lgkmcnt(1)
	v_mfma_f32_32x32x16_bf16 v[18:33], v[196:199], v[200:203], v[18:33]
	v_mfma_f32_32x32x16_bf16 v[2:17], v[212:215], v[200:203], v[2:17]
	v_mfma_f32_32x32x16_bf16 v[50:65], v[204:207], v[208:211], v[50:65]
	v_mfma_f32_32x32x16_bf16 v[34:49], v[216:219], v[208:211], v[34:49]
	s_waitcnt lgkmcnt(0)
	v_mfma_f32_32x32x16_bf16 v[18:33], v[204:207], v[220:223], v[18:33]
	ds_read_b128 v[196:199], v186 offset:64
	ds_read_b128 v[200:203], v188 offset:36928
	ds_read_b128 v[204:207], v186 offset:96
	ds_read_b128 v[208:211], v188 offset:36960
	v_mfma_f32_32x32x16_bf16 v[2:17], v[216:219], v[220:223], v[2:17]
	ds_read_b128 v[212:215], v186 offset:4672
	ds_read_b128 v[216:219], v186 offset:4704
	s_waitcnt lgkmcnt(4)
	v_mfma_f32_32x32x16_bf16 v[50:65], v[196:199], v[200:203], v[50:65]
	s_waitcnt lgkmcnt(1)
	v_mfma_f32_32x32x16_bf16 v[34:49], v[212:215], v[200:203], v[34:49]
	ds_read_b128 v[200:203], v188 offset:41536
	ds_read_b128 v[220:223], v188 offset:41568
	s_waitcnt lgkmcnt(1)
	v_mfma_f32_32x32x16_bf16 v[18:33], v[196:199], v[200:203], v[18:33]
	v_mfma_f32_32x32x16_bf16 v[2:17], v[212:215], v[200:203], v[2:17]
	v_mfma_f32_32x32x16_bf16 v[50:65], v[204:207], v[208:211], v[50:65]
	v_mfma_f32_32x32x16_bf16 v[34:49], v[216:219], v[208:211], v[34:49]
	global_load_dwordx4 v[196:199], v[174:175], off offset:896
	s_nop 0
	global_load_dwordx4 v[174:177], v[176:177], off offset:896
	s_nop 0
	global_load_dwordx4 v[200:203], v[178:179], off offset:896
	s_nop 0
	global_load_dwordx4 v[178:181], v[180:181], off offset:896
	s_nop 0
	global_load_dwordx4 v[208:211], v[66:67], off offset:896
	global_load_dwordx4 v[212:215], v[70:71], off offset:896
	s_nop 0
	global_load_dwordx4 v[66:69], v[68:69], off offset:896
	s_nop 0
	global_load_dwordx4 v[70:73], v[72:73], off offset:896
	s_setprio 1
	s_waitcnt vmcnt(7)
	ds_write_b128 v189, v[196:199] offset:18432
	s_waitcnt vmcnt(6)
	ds_write_b128 v189, v[174:177] offset:23040
	s_waitcnt vmcnt(5)
	ds_write_b128 v189, v[200:203] offset:27648
	s_waitcnt vmcnt(4)
	ds_write_b128 v189, v[178:181] offset:32256
	s_waitcnt vmcnt(3)
	ds_write_b128 v189, v[208:211] offset:55296
	s_waitcnt vmcnt(2)
	ds_write_b128 v189, v[212:215] offset:59904
	s_waitcnt vmcnt(1)
	ds_write_b128 v189, v[66:69] offset:64512
	s_waitcnt vmcnt(0)
	ds_write_b128 v190, v[70:73] offset:32256
	s_waitcnt lgkmcnt(8)
	v_mfma_f32_32x32x16_bf16 v[18:33], v[204:207], v[220:223], v[18:33]
	s_waitcnt lgkmcnt(0)
	s_barrier
	s_setprio 0
	ds_read_b128 v[66:69], v186 offset:18432
	ds_read_b128 v[70:73], v188 offset:55296
	ds_read_b128 v[174:177], v186 offset:18464
	ds_read_b128 v[178:181], v188 offset:55328
	ds_read_b128 v[196:199], v186 offset:23040
	ds_read_b128 v[200:203], v186 offset:23072
	v_mfma_f32_32x32x16_bf16 v[2:17], v[216:219], v[220:223], v[2:17]
	s_waitcnt lgkmcnt(4)
	v_mfma_f32_32x32x16_bf16 v[50:65], v[66:69], v[70:73], v[50:65]
	s_waitcnt lgkmcnt(1)
	v_mfma_f32_32x32x16_bf16 v[34:49], v[196:199], v[70:73], v[34:49]
	ds_read_b128 v[70:73], v188 offset:59904
	ds_read_b128 v[204:207], v188 offset:59936
	s_waitcnt lgkmcnt(1)
	v_mfma_f32_32x32x16_bf16 v[18:33], v[66:69], v[70:73], v[18:33]
	v_mfma_f32_32x32x16_bf16 v[2:17], v[196:199], v[70:73], v[2:17]
	v_mfma_f32_32x32x16_bf16 v[50:65], v[174:177], v[178:181], v[50:65]
	v_mfma_f32_32x32x16_bf16 v[34:49], v[200:203], v[178:181], v[34:49]
	s_waitcnt lgkmcnt(0)
	v_mfma_f32_32x32x16_bf16 v[18:33], v[174:177], v[204:207], v[18:33]
	ds_read_b128 v[66:69], v186 offset:18496
	ds_read_b128 v[70:73], v188 offset:55360
	ds_read_b128 v[174:177], v186 offset:18528
	ds_read_b128 v[178:181], v188 offset:55392
	v_mfma_f32_32x32x16_bf16 v[2:17], v[200:203], v[204:207], v[2:17]
	ds_read_b128 v[196:199], v186 offset:23104
	ds_read_b128 v[200:203], v186 offset:23136
	s_waitcnt lgkmcnt(4)
	v_mfma_f32_32x32x16_bf16 v[50:65], v[66:69], v[70:73], v[50:65]
	s_waitcnt lgkmcnt(1)
	v_mfma_f32_32x32x16_bf16 v[34:49], v[196:199], v[70:73], v[34:49]
	ds_read_b128 v[70:73], v188 offset:59968
	ds_read_b128 v[204:207], v188 offset:60000
	s_waitcnt lgkmcnt(0)
	s_barrier
	v_mfma_f32_32x32x16_bf16 v[18:33], v[66:69], v[70:73], v[18:33]
	v_mfma_f32_32x32x16_bf16 v[2:17], v[196:199], v[70:73], v[2:17]
	v_mfma_f32_32x32x16_bf16 v[50:65], v[174:177], v[178:181], v[50:65]
	v_mfma_f32_32x32x16_bf16 v[34:49], v[200:203], v[178:181], v[34:49]
	v_mfma_f32_32x32x16_bf16 v[18:33], v[174:177], v[204:207], v[18:33]
	v_mfma_f32_32x32x16_bf16 v[2:17], v[200:203], v[204:207], v[2:17]
	s_cbranch_scc1 .LBB0_1794
	s_cmp_lg_u32 s17, 1
	s_mov_b64 s[4:5], -1
	s_cbranch_scc0 .LBB0_1798
	s_mov_b64 s[4:5], 0
